# G1+A1+nt13 + V2: attention softmax VALU diet (max update/alpha/rescale out of the common path, per-half l, no P swaps with natural-order V tile)
# speedup vs baseline: 1.0085x; 1.0085x over previous
; __device__ __forceinline__ int crow(int r, int hi) { return (r & 3) + 8 * (r >> 2) + 4 * hi; }
; __device__ __forceinline__ int v_rd_base(int lane) { return ((lane & 3) << 3) | (((lane >> 2) & 3) << 6) | (((lane >> 4) & 1) << 5) | (((lane >> 5) & 1) << 8); }
; __device__ __forceinline__ int crow(int r, int hi) { return (r & 3) + 8 * (r >> 2) + 4 * hi; }
; __device__ __forceinline__ int v_rd_base(int lane) { return ((lane & 3) << 3) | (((lane >> 2) & 3) << 6) | (((lane >> 4) & 1) << 5) | (((lane >> 5) & 1) << 8); }
; __device__ __forceinline__ void attn_unit256q(const bf16* __restrict__ Qb, const unsigned char* __restrict__ Kc, const unsigned char* __restrict__ Kl, const float* __restrict__ Sc, const float* __restrict__ Sl, ...
;     ...
;   const int kx = (r32 & 7) << 4;
;   const lds_cptr kp0 = shm3 + LDS_K + r32 * 128, vp0 = shm3 + LDS_V + v_rd_base(lane);
;   float ksn0 = Sc[0], ksn1 = Sc[1];
;   constexpr float BIAS = 12582912.f;
;   i32x16 bini;
; #pragma unroll
;   for (int r = 0; r < 16; ++r) bini[r] = 0x4B400000;
;   asm volatile("" : "+v"(bini));
; __global__ void __launch_bounds__(NWAVES * 64, 2) fwd_kernel(Args args) {
;     ...
;         xcd_barrier(bar);
;         float* sml = (float*)((char*)lds + ATT_SML_OFF);
;         for (int i = 0;; ++i) {
;             const long Lu = (long)i * G + bx; if (Lu >= 2176) break;
;             int b, h, n, qrow0, seq;
;             if (Lu < 2048) { const int xcd = (int)(Lu & 7), k = (int)(Lu >> 3), bh = xcd * 8 + (k >> 5), r = k & 31; b = bh >> 4; h = bh & 15; n = r >> 4; qrow0 = b * 4096 + (r & 15) * 256; seq = 4352; }
;             else { const int e = (int)Lu - 2048; b = e >> 5; h = (e >> 1) & 15; n = e & 1; qrow0 = MLAT + b * 256; seq = 256; }
;             const size_t hm = (size_t)(h * 2 + n) * 17408, qk0 = hm * 128, v0 = (size_t)h * 17408 * 256; const size_t crow = MLAT + b * 256, lrow = b * 4096;
;             att2::attn_unit256q(QH + qk0 + (size_t)qrow0 * 128, K8 + (hm + crow) * 128, K8 + (hm + lrow) * 128, KSC + (hm + crow) / 32, KSC + (hm + lrow) / 32, VH + v0 + crow * 256, VH + v0 + lrow * 256,
;                                 OB + (size_t)qrow0 * 8192 + n * 4096 + h * 256, seq, (char*)lds + RING_OFF, sml);
.LBB0_527:
	s_or_b64 exec, exec, s[0:1]
	s_add_u32 s22, s30, 0x1ca00000
	v_readlane_b32 s0, v243, 50
	s_addc_u32 s23, s31, 0
	s_ashr_i32 s24, s33, 31
	s_ashr_i32 s25, s0, 31
	s_mov_b32 s5, 0
	v_mov_b64_e32 v[198:199], 0x87f
	v_mov_b32_e32 v201, 0
	s_mov_b32 s26, 0x41000000
	s_mov_b32 s27, 0x42fe0000
	s_mov_b32 s34, 0x40c0c00
	s_mov_b64 s[6:7], 0x80
	s_mov_b64 s[8:9], 0x100
	s_mov_b64 s[10:11], 0x180
	v_mov_b64_e32 v[202:203], 0x7ff
	v_mov_b32_e32 v217, 0x7ffff3
	s_waitcnt lgkmcnt(0)
	v_mov_b32_e32 v2, 0x4b400000
	s_mov_b32 s100, 0x4b400000
	s_mov_b32 s35, 0
	s_barrier
	s_branch .LBB0_530

; #define Q5_MX(w) mx = fmaxf(mx, fmaxf(__builtin_fabsf(blo(w)), __builtin_fabsf(bhi(w))))
; #define Q5_Q2(w0, w1) q8p(blo(w0) * inv, bhi(w0) * inv, blo(w1) * inv, bhi(w1) * inv)
; __device__ __forceinline__ void attn_unit256q(const bf16* __restrict__ Qb, const unsigned char* __restrict__ Kc, const unsigned char* __restrict__ Kl, const float* __restrict__ Sc, const float* __restrict__ Sl, ...
;     ...
;   unsigned koff, voff[4];
;   { const int row = wid * 8 + (lane >> 3); koff = (unsigned)(row * 128 + (((lane & 7) ^ (row & 7)) << 4)); }
; #pragma unroll
;   for (int i = 0; i < 4; ++i) { const int q = wid * 4 + i, st = 2 * q + (lane >> 5), kk = (st >> 3) * 8 + ((lane & 31) >> 2), k = (kk & ~0xC) | ((kk & 4) << 1) | ((kk & 8) >> 1), c = (st & 7) * 32 + (lane & 3) * 8;
;     voff[i] = (unsigned)(k * 512 + c * 2); }
;   const unsigned kdst = lds0 + LDS_K + wid * 1024, vdst = lds0 + LDS_V + wid * 4096;
;   const int NT = seq / 64;
;   i32x4v qr[4]; float Cq, thrq;
;   { const u32x4* Qw = (const u32x4*)(Qb + (size_t)(wid * 32 + r32) * 128 + hi * 16);
;     u32x4 qa[4], qb[4];
; #pragma unroll
;     for (int d0 = 0; d0 < 4; ++d0) { qa[d0] = Qw[d0 * 4]; qb[d0] = Qw[d0 * 4 + 1]; }
;     float mx = 0.f;
;     ...
; #pragma unroll
;     for (int d0 = 0; d0 < 4; ++d0) { Q5_MX(qa[d0].x); Q5_MX(qa[d0].y); Q5_MX(qa[d0].z); Q5_MX(qa[d0].w); Q5_MX(qb[d0].x); Q5_MX(qb[d0].y); Q5_MX(qb[d0].z); Q5_MX(qb[d0].w); }
;     ...
;     { auto rr = __builtin_amdgcn_permlane32_swap(__float_as_uint(mx), __float_as_uint(mx), false, false); mx = fmaxf(__uint_as_float(rr[0]), __uint_as_float(rr[1])); }
;     const float inv = mx > 0.f ? 127.f / mx : 0.f, qs = mx * (1.f / 127.f);
;     Cq = C * qs; thrq = mx > 0.f ? THR / (SCALE * qs) : 3.0e38f;
;     ...
; #pragma unroll
;     for (int d0 = 0; d0 < 4; ++d0) { qr[d0][0] = (int)Q5_Q2(qa[d0].x, qa[d0].y); qr[d0][1] = (int)Q5_Q2(qa[d0].z, qa[d0].w); qr[d0][2] = (int)Q5_Q2(qb[d0].x, qb[d0].y); qr[d0][3] = (int)Q5_Q2(qb[d0].z, qb[d0].w); }
.LBB0_537:
	s_or_b64 exec, exec, s[16:17]
	s_ashr_i32 s21, s20, 31
	s_ashr_i32 s3, s2, 31
	s_add_u32 s74, s18, s20
	s_addc_u32 s75, 0, s21
	s_lshl_b64 s[16:17], s[74:75], 7
	v_readlane_b32 s36, v243, 55
	v_readlane_b32 s37, v243, 56
	s_add_u32 s16, s36, s16
	s_addc_u32 s17, s37, s17
	s_add_u32 s76, s18, s2
	s_addc_u32 s77, 0, s3
	s_lshl_b64 s[18:19], s[76:77], 7
	s_add_u32 s72, s36, s18
	s_addc_u32 s73, s37, s19
	s_lshr_b64 s[18:19], s[74:75], 3
	s_add_u32 s18, s22, s18
	s_addc_u32 s19, s23, s19
	s_lshr_b64 s[74:75], s[76:77], 3
	s_add_u32 s74, s22, s74
	s_addc_u32 s75, s23, s75
	s_mul_i32 s76, s13, 0x880000
	s_add_u32 s76, s40, s76
	s_addc_u32 s77, s41, 0
	s_lshl_b64 s[20:21], s[20:21], 9
	s_add_u32 s20, s76, s20
	s_addc_u32 s21, s77, s21
	s_lshl_b64 s[2:3], s[2:3], 9
	v_bfe_u32 v71, v3, 3, 3
	s_add_u32 s76, s76, s2
	v_lshlrev_b32_e32 v72, 7, v71
	v_bitop3_b32 v71, v71, v3, 7 bitop3:0x78
	s_addc_u32 s77, s77, s3
	v_lshlrev_b32_e32 v71, 4, v71
	s_lshl_b32 s2, s4, 3
	v_lshrrev_b32_e32 v73, 2, v24
	s_lshl_b32 s80, s4, 10
	v_or_b32_e32 v73, s2, v73
	v_lshrrev_b32_e32 v74, 1, v24
	s_lshl_b32 s2, s4, 2
	v_or3_b32 v200, v71, v72, s80
	v_div_scale_f32 v71, s[84:85], v7, v7, s27
	v_and_b32_e32 v74, 8, v74
	s_and_b32 s2, s2, 4
	v_rcp_f32_e32 v72, v71
	v_and_b32_e32 v74, 32, v3
	v_lshlrev_b32_e32 v75, 3, v3
	v_and_or_b32 v74, v75, 24, v74
	v_lshlrev_b32_e32 v74, 1, v74
	v_lshl_or_b32 v204, v73, 9, v74
	v_fma_f32 v73, -v71, v72, 1.0
	v_fmac_f32_e32 v72, v73, v72
	v_div_scale_f32 v73, vcc, s27, v7, s27
	v_mul_f32_e32 v74, v73, v72
	v_fma_f32 v75, -v71, v74, v73
	v_fmac_f32_e32 v74, v75, v72
	v_fma_f32 v71, -v71, v74, v73
	v_div_fmas_f32 v71, v71, v72, v74
	v_div_fixup_f32 v7, v71, v7, s27
	v_cndmask_b32_e64 v71, 0, v7, s[0:1]
	v_mul_f32_e32 v7, v71, v25
	v_mul_f32_e32 v25, v71, v26
	v_mul_f32_e32 v26, v71, v27
	v_mul_f32_e32 v27, v71, v28
	v_rndne_f32_e32 v25, v25
	v_rndne_f32_e32 v7, v7
	v_cvt_i32_f32_e32 v25, v25
	v_rndne_f32_e32 v26, v26
	v_rndne_f32_e32 v27, v27
	v_cvt_i32_f32_e32 v7, v7
	v_cvt_i32_f32_sdwa v26, v26 dst_sel:WORD_1 dst_unused:UNUSED_PAD src0_sel:DWORD
	v_cvt_i32_f32_e32 v27, v27
	v_lshlrev_b32_e32 v25, 8, v25
	v_and_b32_e32 v25, 0xff00, v25
	v_and_b32_e32 v26, 0xff0000, v26
	v_perm_b32 v7, v27, v7, s34
	v_or3_b32 v164, v7, v25, v26
	v_mul_f32_e32 v25, v71, v30
	v_mul_f32_e32 v7, v71, v29
	v_mul_f32_e32 v26, v71, v31
	v_mul_f32_e32 v27, v71, v32
	v_rndne_f32_e32 v25, v25
	v_rndne_f32_e32 v7, v7
	v_cvt_i32_f32_e32 v25, v25
	v_rndne_f32_e32 v26, v26
	v_rndne_f32_e32 v27, v27
	v_cvt_i32_f32_e32 v7, v7
	v_cvt_i32_f32_sdwa v26, v26 dst_sel:WORD_1 dst_unused:UNUSED_PAD src0_sel:DWORD
	v_cvt_i32_f32_e32 v27, v27
	v_lshlrev_b32_e32 v25, 8, v25
	v_and_b32_e32 v25, 0xff00, v25
	v_and_b32_e32 v26, 0xff0000, v26
	v_perm_b32 v7, v27, v7, s34
	v_or3_b32 v165, v7, v25, v26
	v_mul_f32_e32 v25, v71, v34
	v_mul_f32_e32 v7, v71, v33
	v_mul_f32_e32 v26, v71, v35
	v_mul_f32_e32 v27, v71, v36
	v_rndne_f32_e32 v25, v25
	v_rndne_f32_e32 v7, v7
	v_cvt_i32_f32_e32 v25, v25
	v_rndne_f32_e32 v26, v26
	v_rndne_f32_e32 v27, v27
	v_cvt_i32_f32_e32 v7, v7
	v_cvt_i32_f32_sdwa v26, v26 dst_sel:WORD_1 dst_unused:UNUSED_PAD src0_sel:DWORD
	v_cvt_i32_f32_e32 v27, v27
	v_lshlrev_b32_e32 v25, 8, v25
	v_and_b32_e32 v25, 0xff00, v25
	v_and_b32_e32 v26, 0xff0000, v26
	v_perm_b32 v7, v27, v7, s34
	v_or3_b32 v166, v7, v25, v26
	v_mul_f32_e32 v25, v71, v38
	v_mul_f32_e32 v7, v71, v37
	v_mul_f32_e32 v26, v71, v39
	v_mul_f32_e32 v27, v71, v40
	v_rndne_f32_e32 v25, v25
	v_rndne_f32_e32 v7, v7
	v_cvt_i32_f32_e32 v25, v25
	v_rndne_f32_e32 v26, v26
	v_rndne_f32_e32 v27, v27
	v_cvt_i32_f32_e32 v7, v7
	v_cvt_i32_f32_sdwa v26, v26 dst_sel:WORD_1 dst_unused:UNUSED_PAD src0_sel:DWORD
	v_cvt_i32_f32_e32 v27, v27
	v_lshlrev_b32_e32 v25, 8, v25
	v_and_b32_e32 v25, 0xff00, v25
	v_and_b32_e32 v26, 0xff0000, v26
	v_perm_b32 v7, v27, v7, s34
	v_or3_b32 v167, v7, v25, v26
	v_mul_f32_e32 v25, v71, v42
	v_mul_f32_e32 v7, v71, v41
	v_mul_f32_e32 v26, v71, v43
	v_mul_f32_e32 v27, v71, v44
	v_rndne_f32_e32 v25, v25
	v_rndne_f32_e32 v7, v7
	v_cvt_i32_f32_e32 v25, v25
	v_rndne_f32_e32 v26, v26
	v_rndne_f32_e32 v27, v27
	v_cvt_i32_f32_e32 v7, v7
	v_cvt_i32_f32_sdwa v26, v26 dst_sel:WORD_1 dst_unused:UNUSED_PAD src0_sel:DWORD
	v_cvt_i32_f32_e32 v27, v27
	v_lshlrev_b32_e32 v25, 8, v25
	v_and_b32_e32 v25, 0xff00, v25
	v_and_b32_e32 v26, 0xff0000, v26
	v_perm_b32 v7, v27, v7, s34
	v_or3_b32 v168, v7, v25, v26
	v_mul_f32_e32 v25, v71, v46
	v_mul_f32_e32 v7, v71, v45
	v_mul_f32_e32 v26, v71, v47
	v_mul_f32_e32 v27, v71, v48
	v_rndne_f32_e32 v25, v25
	v_rndne_f32_e32 v7, v7
	v_cvt_i32_f32_e32 v25, v25
	v_rndne_f32_e32 v26, v26
	v_rndne_f32_e32 v27, v27
	v_cvt_i32_f32_e32 v7, v7
	v_cvt_i32_f32_sdwa v26, v26 dst_sel:WORD_1 dst_unused:UNUSED_PAD src0_sel:DWORD
	v_cvt_i32_f32_e32 v27, v27
	v_lshlrev_b32_e32 v25, 8, v25
	v_and_b32_e32 v25, 0xff00, v25
	v_and_b32_e32 v26, 0xff0000, v26
	v_perm_b32 v7, v27, v7, s34
	v_mul_f32_e32 v20, v71, v20
	v_or3_b32 v169, v7, v25, v26
	v_mul_f32_e32 v7, v71, v49
	v_mul_f32_e32 v25, v71, v68
	v_mul_f32_e32 v26, v71, v69
	v_rndne_f32_e32 v20, v20
	v_rndne_f32_e32 v7, v7
	v_cvt_i32_f32_e32 v20, v20
	v_rndne_f32_e32 v25, v25
	v_rndne_f32_e32 v26, v26
	v_cvt_i32_f32_e32 v7, v7
	v_cvt_i32_f32_sdwa v25, v25 dst_sel:WORD_1 dst_unused:UNUSED_PAD src0_sel:DWORD
	v_cvt_i32_f32_e32 v26, v26
	v_lshlrev_b32_e32 v20, 8, v20
	v_and_b32_e32 v20, 0xff00, v20
	v_and_b32_e32 v25, 0xff0000, v25
	v_perm_b32 v7, v26, v7, s34
	v_or3_b32 v170, v7, v20, v25
	v_mul_f32_e32 v20, v71, v65
	v_mul_f32_e32 v7, v71, v64
	v_mul_f32_e32 v25, v71, v66
	v_mul_f32_e32 v26, v71, v67
	v_rndne_f32_e32 v20, v20
; __device__ __forceinline__ int v_rd_base(int lane) { return ((lane & 3) << 3) | (((lane >> 2) & 3) << 6) | (((lane >> 4) & 1) << 5) | (((lane >> 5) & 1) << 8); }
; __device__ __forceinline__ int v_rd_base(int lane) { return ((lane & 3) << 3) | (((lane >> 2) & 3) << 6) | (((lane >> 4) & 1) << 5) | (((lane >> 5) & 1) << 8); }
; #define Q5_Q2(w0, w1) q8p(blo(w0) * inv, bhi(w0) * inv, blo(w1) * inv, bhi(w1) * inv)
; __device__ __forceinline__ void attn_unit256q(const bf16* __restrict__ Qb, const unsigned char* __restrict__ Kc, const unsigned char* __restrict__ Kl, const float* __restrict__ Sc, const float* __restrict__ Sl, ...
;     ...
;     for (int d0 = 0; d0 < 4; ++d0) { qr[d0][0] = (int)Q5_Q2(qa[d0].x, qa[d0].y); qr[d0][1] = (int)Q5_Q2(qa[d0].z, qa[d0].w); qr[d0][2] = (int)Q5_Q2(qb[d0].x, qb[d0].y); qr[d0][3] = (int)Q5_Q2(qb[d0].z, qb[d0].w); }
;     ...
;   }
;   { glds16((const char*)Kc + koff, (unsigned)__builtin_amdgcn_readfirstlane(kdst));
; #pragma unroll
;     for (int i = 0; i < 4; ++i) glds16((const char*)Vc + voff[i], (unsigned)__builtin_amdgcn_readfirstlane(vdst + i * 1024)); }
;   const int kx = (r32 & 7) << 4;
;   const lds_cptr kp0 = shm3 + LDS_K + r32 * 128, vp0 = shm3 + LDS_V + v_rd_base(lane);
;   float ksn0 = Sc[0], ksn1 = Sc[1];
	v_rndne_f32_e32 v7, v7
	v_cvt_i32_f32_e32 v20, v20
	v_rndne_f32_e32 v25, v25
	v_rndne_f32_e32 v26, v26
	v_cvt_i32_f32_e32 v7, v7
	v_cvt_i32_f32_sdwa v25, v25 dst_sel:WORD_1 dst_unused:UNUSED_PAD src0_sel:DWORD
	v_cvt_i32_f32_e32 v26, v26
	v_lshlrev_b32_e32 v20, 8, v20
	v_and_b32_e32 v20, 0xff00, v20
	v_and_b32_e32 v25, 0xff0000, v25
	v_perm_b32 v7, v26, v7, s34
	v_or3_b32 v171, v7, v20, v25
	v_mul_f32_e32 v20, v71, v61
	v_mul_f32_e32 v7, v71, v60
	v_mul_f32_e32 v25, v71, v62
	v_mul_f32_e32 v26, v71, v63
	v_rndne_f32_e32 v20, v20
	v_rndne_f32_e32 v7, v7
	v_cvt_i32_f32_e32 v20, v20
	v_rndne_f32_e32 v25, v25
	v_rndne_f32_e32 v26, v26
	v_cvt_i32_f32_e32 v7, v7
	v_cvt_i32_f32_sdwa v25, v25 dst_sel:WORD_1 dst_unused:UNUSED_PAD src0_sel:DWORD
	v_cvt_i32_f32_e32 v26, v26
	v_lshlrev_b32_e32 v20, 8, v20
	v_and_b32_e32 v20, 0xff00, v20
	v_and_b32_e32 v25, 0xff0000, v25
	v_perm_b32 v7, v26, v7, s34
	v_or3_b32 v172, v7, v20, v25
	v_mul_f32_e32 v20, v71, v57
	v_mul_f32_e32 v7, v71, v56
	v_mul_f32_e32 v25, v71, v58
	v_mul_f32_e32 v26, v71, v59
	v_rndne_f32_e32 v20, v20
	v_rndne_f32_e32 v7, v7
	v_cvt_i32_f32_e32 v20, v20
	v_rndne_f32_e32 v25, v25
	v_rndne_f32_e32 v26, v26
	v_cvt_i32_f32_e32 v7, v7
	v_cvt_i32_f32_sdwa v25, v25 dst_sel:WORD_1 dst_unused:UNUSED_PAD src0_sel:DWORD
	v_cvt_i32_f32_e32 v26, v26
	v_lshlrev_b32_e32 v20, 8, v20
	v_and_b32_e32 v20, 0xff00, v20
	v_and_b32_e32 v25, 0xff0000, v25
	v_perm_b32 v7, v26, v7, s34
	v_or3_b32 v173, v7, v20, v25
	v_mul_f32_e32 v20, v71, v53
	v_mul_f32_e32 v7, v71, v52
	v_mul_f32_e32 v25, v71, v54
	v_mul_f32_e32 v26, v71, v55
	v_rndne_f32_e32 v20, v20
	v_rndne_f32_e32 v7, v7
	v_cvt_i32_f32_e32 v20, v20
	v_rndne_f32_e32 v25, v25
	v_rndne_f32_e32 v26, v26
	v_cvt_i32_f32_e32 v7, v7
	v_cvt_i32_f32_sdwa v25, v25 dst_sel:WORD_1 dst_unused:UNUSED_PAD src0_sel:DWORD
	v_cvt_i32_f32_e32 v26, v26
	v_lshlrev_b32_e32 v20, 8, v20
	v_and_b32_e32 v20, 0xff00, v20
	v_and_b32_e32 v25, 0xff0000, v25
	v_perm_b32 v7, v26, v7, s34
	v_or3_b32 v174, v7, v20, v25
	v_mul_f32_e32 v20, v71, v23
	v_mul_f32_e32 v7, v71, v22
	v_mul_f32_e32 v22, v71, v50
	v_mul_f32_e32 v23, v71, v51
	v_rndne_f32_e32 v20, v20
	v_rndne_f32_e32 v7, v7
	v_cvt_i32_f32_e32 v20, v20
	v_rndne_f32_e32 v22, v22
	v_rndne_f32_e32 v23, v23
	v_cvt_i32_f32_e32 v7, v7
	v_cvt_i32_f32_sdwa v22, v22 dst_sel:WORD_1 dst_unused:UNUSED_PAD src0_sel:DWORD
	v_cvt_i32_f32_e32 v23, v23
	v_lshlrev_b32_e32 v20, 8, v20
	v_and_b32_e32 v20, 0xff00, v20
	v_and_b32_e32 v22, 0xff0000, v22
	v_perm_b32 v7, v23, v7, s34
	v_or3_b32 v175, v7, v20, v22
	v_mul_f32_e32 v7, v71, v17
	v_mul_f32_e32 v17, v71, v18
	v_mul_f32_e32 v18, v71, v19
	v_mul_f32_e32 v19, v71, v21
	v_rndne_f32_e32 v17, v17
	v_rndne_f32_e32 v7, v7
	v_cvt_i32_f32_e32 v17, v17
	v_rndne_f32_e32 v18, v18
	v_rndne_f32_e32 v19, v19
	v_cvt_i32_f32_e32 v7, v7
	v_cvt_i32_f32_sdwa v18, v18 dst_sel:WORD_1 dst_unused:UNUSED_PAD src0_sel:DWORD
	v_cvt_i32_f32_e32 v19, v19
	v_lshlrev_b32_e32 v17, 8, v17
	v_and_b32_e32 v17, 0xff00, v17
	v_and_b32_e32 v18, 0xff0000, v18
	v_perm_b32 v7, v19, v7, s34
	v_or3_b32 v176, v7, v17, v18
	v_mul_f32_e32 v7, v71, v13
	v_mul_f32_e32 v13, v71, v14
	v_mul_f32_e32 v14, v71, v15
	v_mul_f32_e32 v15, v71, v16
	v_rndne_f32_e32 v13, v13
	v_rndne_f32_e32 v7, v7
	v_cvt_i32_f32_e32 v13, v13
	v_rndne_f32_e32 v14, v14
	v_rndne_f32_e32 v15, v15
	v_cvt_i32_f32_e32 v7, v7
	v_cvt_i32_f32_sdwa v14, v14 dst_sel:WORD_1 dst_unused:UNUSED_PAD src0_sel:DWORD
	v_cvt_i32_f32_e32 v15, v15
	v_lshlrev_b32_e32 v13, 8, v13
	v_and_b32_e32 v13, 0xff00, v13
	v_and_b32_e32 v14, 0xff0000, v14
	v_perm_b32 v7, v15, v7, s34
	v_or3_b32 v177, v7, v13, v14
	v_mul_f32_e32 v7, v71, v9
	v_mul_f32_e32 v9, v71, v10
	v_mul_f32_e32 v10, v71, v11
	v_mul_f32_e32 v11, v71, v12
	v_rndne_f32_e32 v9, v9
	v_rndne_f32_e32 v7, v7
	v_cvt_i32_f32_e32 v9, v9
	v_rndne_f32_e32 v10, v10
	v_rndne_f32_e32 v11, v11
	v_cvt_i32_f32_e32 v7, v7
	v_cvt_i32_f32_sdwa v10, v10 dst_sel:WORD_1 dst_unused:UNUSED_PAD src0_sel:DWORD
	v_cvt_i32_f32_e32 v11, v11
	s_lshl_b32 s3, s4, 9
	s_lshl_b32 s81, s4, 12
	s_cmp_lg_u32 0, -1
	v_lshlrev_b32_e32 v9, 8, v9
	s_cselect_b32 s4, 0, 0
	v_and_b32_e32 v9, 0xff00, v9
	v_and_b32_e32 v10, 0xff0000, v10
	v_perm_b32 v7, v11, v7, s34
	s_add_i32 s2, s4, s81
	s_add_i32 s83, s80, s4
	v_or3_b32 v178, v7, v9, v10
	v_mul_f32_e32 v10, v71, v6
	v_lshl_add_u64 v[6:7], s[16:17], 0, v[200:201]
	s_mov_b32 s0, m0
	s_mov_b32 m0, s83
	s_nop 0
	global_load_lds_dwordx4 v[6:7], off
	s_mov_b32 m0, s0
	v_mov_b32_e32 v205, v201
	s_add_i32 s82, s2, 0x8000
	v_lshl_add_u64 v[6:7], s[20:21], 0, v[204:205]
	s_mov_b32 s0, m0
	s_mov_b32 m0, s82
	s_nop 0
	global_load_lds_dwordx4 v[6:7], off
	s_mov_b32 m0, s0
	v_mul_f32_e32 v11, v71, v8
	v_lshl_add_u64 v[8:9], v[6:7], 0, s[6:7]
	s_add_i32 s0, s2, 0x8400
	s_mov_b32 s1, m0
	s_mov_b32 m0, s0
	s_nop 0
	global_load_lds_dwordx4 v[8:9], off
	s_mov_b32 m0, s1
	v_lshl_add_u64 v[8:9], v[6:7], 0, s[8:9]
	s_add_i32 s0, s2, 0x8800
	s_mov_b32 s1, m0
	s_mov_b32 m0, s0
	s_nop 0
	global_load_lds_dwordx4 v[8:9], off
	s_mov_b32 m0, s1
	v_lshl_add_u64 v[6:7], v[6:7], 0, s[10:11]
	s_add_i32 s2, s2, 0x8c00
	s_mov_b32 s0, m0
	s_mov_b32 m0, s2
	s_nop 0
	global_load_lds_dwordx4 v[6:7], off
	s_mov_b32 m0, s0
	global_load_dwordx2 v[206:207], v201, s[18:19]
	v_mul_f32_e32 v5, v71, v5
	v_mul_f32_e32 v4, v71, v4
	v_rndne_f32_e32 v6, v10
	v_rndne_f32_e32 v5, v5
	v_cvt_i32_f32_e32 v6, v6
	v_rndne_f32_e32 v7, v11
	v_rndne_f32_e32 v4, v4
	v_cvt_i32_f32_e32 v5, v5
	v_cvt_i32_f32_sdwa v7, v7 dst_sel:WORD_1 dst_unused:UNUSED_PAD src0_sel:DWORD
	v_cvt_i32_f32_e32 v4, v4
	v_lshlrev_b32_e32 v6, 8, v6
	v_and_b32_e32 v219, 63, v3
	v_and_b32_e32 v6, 0xff00, v6
; __device__ __forceinline__ void attn_unit256q(const bf16* __restrict__ Qb, const unsigned char* __restrict__ Kc, const unsigned char* __restrict__ Kl, const float* __restrict__ Sc, const float* __restrict__ Sl, ...
;     ...
;   constexpr float BIAS = 12582912.f;
;   i32x16 bini;
; #pragma unroll
;   for (int r = 0; r < 16; ++r) bini[r] = 0x4B400000;
;   asm volatile("" : "+v"(bini));
;   float m_reg = -1e30f, l_reg = 0.f, alpha = 1.f; f32x16 o[8];
; #pragma unroll
;   for (int d = 0; d < 8; ++d) o[d] = f32x16{};
;   f32x16 p; i32x16 p8; bf16x8 pa0, pa1; float ks0, ks1;
	v_and_b32_e32 v7, 0xff0000, v7
	v_perm_b32 v4, v4, v5, s34
	v_or3_b32 v179, v4, v6, v7
	v_lshlrev_b32_e32 v4, 3, v219
	v_lshlrev_b32_e32 v18, 4, v3
	v_and_b32_e32 v5, 24, v4
	v_and_b32_e32 v6, 0xc0, v18
	v_lshlrev_b32_e32 v3, 1, v3
	v_mov_b32_e32 v16, v2
	v_mov_b32_e32 v17, v2
	v_and_b32_e32 v19, 32, v3
	v_add3_u32 v20, 0, v5, v6
	v_and_b32_e32 v21, 0x100, v4
	v_mov_b32_e32 v3, v2
	v_mov_b32_e32 v4, v2
	v_mov_b32_e32 v5, v2
	v_mov_b32_e32 v6, v2
	v_mov_b32_e32 v7, v2
	v_mov_b32_e32 v8, v2
	v_mov_b32_e32 v9, v2
	v_mov_b32_e32 v10, v2
	v_mov_b32_e32 v11, v2
	v_mov_b32_e32 v12, v2
	v_mov_b32_e32 v13, v2
	v_mov_b32_e32 v14, v2
	v_mov_b32_e32 v15, v2
	v_mov_b64_e32 v[146:147], v[16:17]
	s_movk_i32 s0, 0x70
	s_add_i32 s78, s3, 0
	v_mov_b64_e32 v[144:145], v[14:15]
	v_mov_b64_e32 v[142:143], v[12:13]
	v_mov_b64_e32 v[140:141], v[10:11]
	v_mov_b64_e32 v[138:139], v[8:9]
	v_mov_b64_e32 v[136:137], v[6:7]
	v_mov_b64_e32 v[134:135], v[4:5]
	v_mov_b64_e32 v[132:133], v[2:3]
	v_add3_u32 v3, v20, v19, v21
	v_and_b32_e32 v4, 0x70, v18
	v_bitop3_b32 v21, v218, v18, s0 bitop3:0x78
	s_movk_i32 s0, 0x60
	s_add_i32 s78, s78, 0x20400
	v_lshl_add_u32 v20, v24, 7, 0
	v_bitop3_b32 v22, v218, v4, 32 bitop3:0x36
	v_bitop3_b32 v23, v218, v4, 64 bitop3:0x36
	v_bitop3_b32 v25, v218, v4, s0 bitop3:0x36
	v_mov_b32_e32 v18, v201
	v_mov_b32_e32 v19, v201
	v_mul_f32_e32 v221, 0x3e0293ee, v70
	v_lshl_add_u32 v223, v24, 2, s78
	v_mov_b32_e32 v4, v201
	v_mov_b32_e32 v5, v201
	v_mov_b32_e32 v6, v201
	v_mov_b32_e32 v7, v201
	v_mov_b32_e32 v8, v201
	v_mov_b32_e32 v9, v201
	v_mov_b32_e32 v10, v201
	v_mov_b32_e32 v11, v201
	v_mov_b32_e32 v12, v201
	v_mov_b32_e32 v13, v201
	v_mov_b32_e32 v14, v201
	v_mov_b32_e32 v15, v201
	v_mov_b32_e32 v16, v201
	v_mov_b32_e32 v17, v201
	v_add_u32_e32 v225, v20, v21
	v_add_u32_e32 v226, v20, v22
	v_add_u32_e32 v227, v20, v23
	v_add_u32_e32 v228, v20, v25
	v_mov_b64_e32 v[130:131], v[18:19]
	v_mov_b64_e32 v[114:115], v[18:19]
	v_mov_b64_e32 v[98:99], v[18:19]
	v_mov_b64_e32 v[82:83], v[18:19]
	v_mov_b64_e32 v[66:67], v[18:19]
	v_mov_b64_e32 v[50:51], v[18:19]
	v_mov_b64_e32 v[34:35], v[18:19]
	s_mov_b32 s79, 2
	v_add_u32_e32 v222, 0x8000, v3
	s_add_i32 s84, s70, -1
	v_cmp_gt_u32_e64 s[0:1], 32, v219
	v_mov_b32_e32 v224, 0
	v_mov_b32_e32 v237, 0xf149f2ca
	v_mul_f32_e32 v255, v221, v237
	v_mov_b64_e32 v[128:129], v[16:17]
	v_mov_b64_e32 v[126:127], v[14:15]
	v_mov_b64_e32 v[124:125], v[12:13]
	v_mov_b64_e32 v[122:123], v[10:11]
	v_mov_b64_e32 v[120:121], v[8:9]
	v_mov_b64_e32 v[118:119], v[6:7]
	v_mov_b64_e32 v[116:117], v[4:5]
	v_mov_b64_e32 v[112:113], v[16:17]
	v_mov_b64_e32 v[110:111], v[14:15]
	v_mov_b64_e32 v[108:109], v[12:13]
	v_mov_b64_e32 v[106:107], v[10:11]
	v_mov_b64_e32 v[104:105], v[8:9]
	v_mov_b64_e32 v[102:103], v[6:7]
	v_mov_b64_e32 v[100:101], v[4:5]
	v_mov_b64_e32 v[96:97], v[16:17]
	v_mov_b64_e32 v[94:95], v[14:15]
	v_mov_b64_e32 v[92:93], v[12:13]
	v_mov_b64_e32 v[90:91], v[10:11]
	v_mov_b64_e32 v[88:89], v[8:9]
	v_mov_b64_e32 v[86:87], v[6:7]
	v_mov_b64_e32 v[84:85], v[4:5]
	v_mov_b64_e32 v[80:81], v[16:17]
	v_mov_b64_e32 v[78:79], v[14:15]
	v_mov_b64_e32 v[76:77], v[12:13]
	v_mov_b64_e32 v[74:75], v[10:11]
	v_mov_b64_e32 v[72:73], v[8:9]
	v_mov_b64_e32 v[70:71], v[6:7]
	v_mov_b64_e32 v[68:69], v[4:5]
	v_mov_b64_e32 v[64:65], v[16:17]
	v_mov_b64_e32 v[62:63], v[14:15]
	v_mov_b64_e32 v[60:61], v[12:13]
	v_mov_b64_e32 v[58:59], v[10:11]
	v_mov_b64_e32 v[56:57], v[8:9]
	v_mov_b64_e32 v[54:55], v[6:7]
	v_mov_b64_e32 v[52:53], v[4:5]
	v_mov_b64_e32 v[48:49], v[16:17]
	v_mov_b64_e32 v[46:47], v[14:15]
	v_mov_b64_e32 v[44:45], v[12:13]
	v_mov_b64_e32 v[42:43], v[10:11]
	v_mov_b64_e32 v[40:41], v[8:9]
	v_mov_b64_e32 v[38:39], v[6:7]
	v_mov_b64_e32 v[36:37], v[4:5]
	v_mov_b64_e32 v[32:33], v[16:17]
	v_mov_b64_e32 v[30:31], v[14:15]
	v_mov_b64_e32 v[28:29], v[12:13]
	v_mov_b64_e32 v[26:27], v[10:11]
	v_mov_b64_e32 v[24:25], v[8:9]
	v_mov_b64_e32 v[22:23], v[6:7]
	v_mov_b64_e32 v[20:21], v[4:5]
.LBB0_538:
	s_add_i32 s2, s79, -1
	s_min_u32 s85, s2, s84
	s_lshl_b32 s4, s85, 6
	s_cmp_lt_u32 s85, 4
	s_cselect_b64 s[2:3], -1, 0
	s_add_i32 s88, s4, 0xffffff00
	s_and_b64 s[86:87], s[2:3], exec
	s_cselect_b32 s4, s4, s88
	s_cselect_b32 s88, s17, s73
	s_cselect_b32 s89, s16, s72
	s_lshl_b64 s[86:87], s[4:5], 7
	s_add_u32 s86, s89, s86
	s_addc_u32 s87, s88, s87
	s_lshl_b32 s88, s85, 1
	s_mov_b32 s89, s5
	s_lshl_b64 s[88:89], s[88:89], 2
	s_add_u32 s85, s18, s88
	s_addc_u32 s90, s19, s89
	s_add_u32 s88, s74, s88
	s_addc_u32 s89, s75, s89
	s_add_u32 s88, s88, 0xffffffe0
	s_addc_u32 s89, s89, -1
	s_and_b64 s[2:3], s[2:3], exec
	s_cselect_b32 s3, s90, s89
	s_cselect_b32 s2, s85, s88
	s_waitcnt vmcnt(0) lgkmcnt(0)
	s_barrier
	s_waitcnt vmcnt(0)
	global_load_dwordx2 v[208:209], v201, s[2:3]
	s_cselect_b32 s85, s21, s77
	s_cselect_b32 s88, s20, s76
	s_lshl_b64 s[2:3], s[4:5], 9
	s_add_u32 s2, s88, s2
	ds_read_b128 v[180:183], v225
	ds_read_b128 v[184:187], v226
	s_addc_u32 s3, s85, s3
	s_cmp_lg_u32 0, -1
	s_cselect_b32 s4, 0, 0
	s_add_i32 s85, s4, s80
	s_add_i32 s4, s4, s81
	s_addk_i32 s85, 0x4000
	s_add_i32 s88, s4, 0x10000
	s_waitcnt lgkmcnt(1)
	v_mfma_i32_32x32x32_i8 v[148:163], v[180:183], v[164:167], v[132:147]
	ds_read_b128 v[180:183], v227
	v_lshl_add_u64 v[188:189], s[86:87], 0, v[200:201]
	s_mov_b32 s86, m0
	s_mov_b32 m0, s85
	s_nop 0
	global_load_lds_dwordx4 v[188:189], off
	s_mov_b32 m0, s86
	v_lshl_add_u64 v[192:193], s[2:3], 0, v[204:205]
	s_mov_b32 s2, m0
	s_mov_b32 m0, s88
	s_nop 0
	global_load_lds_dwordx4 v[192:193], off
	s_mov_b32 m0, s2
	s_waitcnt lgkmcnt(1)
	v_mfma_i32_32x32x32_i8 v[148:163], v[184:187], v[168:171], v[148:163]
	ds_read_b128 v[188:191], v228
	v_lshl_add_u64 v[184:185], v[192:193], 0, s[6:7]
	s_add_i32 s2, s4, 0x10400
	s_mov_b32 s3, m0
	s_mov_b32 m0, s2
	s_nop 0
	global_load_lds_dwordx4 v[184:185], off
	s_mov_b32 m0, s3
	v_lshl_add_u64 v[184:185], v[192:193], 0, s[8:9]
	s_add_i32 s2, s4, 0x10800
	s_mov_b32 s3, m0
	s_mov_b32 m0, s2
	s_nop 0
	global_load_lds_dwordx4 v[184:185], off
	s_mov_b32 m0, s3
	s_waitcnt lgkmcnt(1)
	v_mfma_i32_32x32x32_i8 v[148:163], v[180:183], v[172:175], v[148:163]
	v_lshl_add_u64 v[180:181], v[192:193], 0, s[10:11]
	s_add_i32 s4, s4, 0x10c00
	s_mov_b32 s2, m0
	s_mov_b32 m0, s4
	s_nop 0
	global_load_lds_dwordx4 v[180:181], off
	s_mov_b32 m0, s2
	ds_read_b64_tr_b16 v[184:185], v3 offset:32768
	ds_read_b64_tr_b16 v[186:187], v3 offset:36864
	s_waitcnt lgkmcnt(2)
	v_mfma_i32_32x32x32_i8 v[148:163], v[188:191], v[176:179], v[148:163]
	ds_read_b64_tr_b16 v[180:181], v3 offset:33280
	ds_read_b64_tr_b16 v[182:183], v3 offset:37376
	s_nop 9
	v_max3_f32 v188, v148, v149, v150
	v_max3_f32 v189, v151, v152, v153
	v_max3_f32 v190, v154, v155, v156
	v_max3_f32 v191, v157, v158, v159
	v_max3_f32 v192, v160, v161, v162
	v_max3_f32 v188, v188, v189, v190
	v_max3_f32 v191, v191, v192, v163
	v_max_f32_e32 v188, v188, v191
	v_add_f32_e32 v188, 0xcb400000, v188
	v_fma_f32 v189, v206, v188, -v237
	v_cmp_gt_f32_e32 vcc, v189, v220
	s_cbranch_vccnz .Lv2_rare_h1
.Lv2_back_h1:
	v_mul_f32_e32 v189, v221, v206
	v_fma_f32 v190, s100, v189, v255
	v_fma_f32 v148, v148, v189, -v190
	v_fma_f32 v149, v149, v189, -v190
	v_exp_f32_e32 v148, v148
	v_fma_f32 v150, v150, v189, -v190
	v_exp_f32_e32 v149, v149
	v_fma_f32 v151, v151, v189, -v190
	v_exp_f32_e32 v150, v150
	v_fma_f32 v152, v152, v189, -v190
	v_exp_f32_e32 v151, v151
	v_fma_f32 v153, v153, v189, -v190
	v_exp_f32_e32 v152, v152
	v_fma_f32 v154, v154, v189, -v190
	v_exp_f32_e32 v153, v153
	v_fma_f32 v155, v155, v189, -v190
	v_exp_f32_e32 v154, v154
	v_fma_f32 v156, v156, v189, -v190
	v_exp_f32_e32 v155, v155
	v_fma_f32 v157, v157, v189, -v190
	v_exp_f32_e32 v156, v156
	v_fma_f32 v158, v158, v189, -v190
	v_exp_f32_e32 v157, v157
	v_fma_f32 v159, v159, v189, -v190
	v_exp_f32_e32 v158, v158
	v_fma_f32 v160, v160, v189, -v190
	v_exp_f32_e32 v159, v159
	v_fma_f32 v161, v161, v189, -v190
	v_exp_f32_e32 v160, v160
	v_fma_f32 v162, v162, v189, -v190
	v_exp_f32_e32 v161, v161
	v_fma_f32 v163, v163, v189, -v190
	v_exp_f32_e32 v162, v162
	v_exp_f32_e32 v163, v163
	v_add_f32_e32 v188, v148, v149
	v_add_f32_e32 v189, v150, v151
	v_add_f32_e32 v190, v152, v153
	v_add_f32_e32 v191, v154, v155
	v_add_f32_e32 v192, v156, v157
	v_add_f32_e32 v193, v158, v159
	v_add_f32_e32 v194, v160, v161
	v_add_f32_e32 v195, v162, v163
	v_add_f32_e32 v188, v188, v189
	v_add_f32_e32 v190, v190, v191
	v_add_f32_e32 v192, v192, v193
	v_add_f32_e32 v194, v194, v195
	v_add_f32_e32 v188, v188, v190
	v_add_f32_e32 v192, v192, v194
	v_add_f32_e32 v188, v188, v192
	v_add_f32_e32 v224, v224, v188
	v_cvt_pk_bf16_f32 v155, v154, v155
	v_cvt_pk_bf16_f32 v154, v152, v153
	v_cvt_pk_bf16_f32 v152, v148, v149
	v_cvt_pk_bf16_f32 v153, v150, v151
	v_cvt_pk_bf16_f32 v148, v156, v157
	v_cvt_pk_bf16_f32 v149, v158, v159
	v_cvt_pk_bf16_f32 v150, v160, v161
	v_cvt_pk_bf16_f32 v151, v162, v163
	s_waitcnt lgkmcnt(2)
	v_mfma_f32_32x32x16_bf16 v[4:19], v[152:155], v[184:187], v[4:19]
	ds_read_b64_tr_b16 v[156:157], v3 offset:33792
	ds_read_b64_tr_b16 v[158:159], v3 offset:37888
	s_waitcnt lgkmcnt(2)
	v_mfma_f32_32x32x16_bf16 v[116:131], v[152:155], v[180:183], v[116:131]
	ds_read_b64_tr_b16 v[160:161], v3 offset:34304
	ds_read_b64_tr_b16 v[162:163], v3 offset:38400
	s_waitcnt lgkmcnt(2)
	v_mfma_f32_32x32x16_bf16 v[100:115], v[152:155], v[156:159], v[100:115]
	ds_read_b64_tr_b16 v[156:157], v3 offset:34816
	ds_read_b64_tr_b16 v[158:159], v3 offset:38912
	s_waitcnt lgkmcnt(2)
	v_mfma_f32_32x32x16_bf16 v[84:99], v[152:155], v[160:163], v[84:99]
	ds_read_b64_tr_b16 v[160:161], v3 offset:35328
	ds_read_b64_tr_b16 v[162:163], v3 offset:39424
	s_waitcnt lgkmcnt(2)
	v_mfma_f32_32x32x16_bf16 v[68:83], v[152:155], v[156:159], v[68:83]
	ds_read_b64_tr_b16 v[156:157], v3 offset:35840
	ds_read_b64_tr_b16 v[158:159], v3 offset:39936
	s_waitcnt lgkmcnt(2)
	v_mfma_f32_32x32x16_bf16 v[52:67], v[152:155], v[160:163], v[52:67]
	ds_read_b64_tr_b16 v[160:161], v3 offset:36352
	ds_read_b64_tr_b16 v[162:163], v3 offset:40448
	s_waitcnt lgkmcnt(2)
	v_mfma_f32_32x32x16_bf16 v[36:51], v[152:155], v[156:159], v[36:51]
	ds_read_b64_tr_b16 v[156:157], v3 offset:40960
	ds_read_b64_tr_b16 v[158:159], v3 offset:45056
	s_waitcnt lgkmcnt(2)
	v_mfma_f32_32x32x16_bf16 v[20:35], v[152:155], v[160:163], v[20:35]
	ds_read_b64_tr_b16 v[152:153], v3 offset:41472
	ds_read_b64_tr_b16 v[154:155], v3 offset:45568
	s_waitcnt lgkmcnt(2)
	v_mfma_f32_32x32x16_bf16 v[4:19], v[148:151], v[156:159], v[4:19]
	ds_read_b64_tr_b16 v[156:157], v3 offset:41984
	ds_read_b64_tr_b16 v[158:159], v3 offset:46080
	s_waitcnt lgkmcnt(2)
	v_mfma_f32_32x32x16_bf16 v[116:131], v[148:151], v[152:155], v[116:131]
	ds_read_b64_tr_b16 v[152:153], v3 offset:42496
	ds_read_b64_tr_b16 v[154:155], v3 offset:46592
	s_waitcnt lgkmcnt(2)
	v_mfma_f32_32x32x16_bf16 v[100:115], v[148:151], v[156:159], v[100:115]
	ds_read_b64_tr_b16 v[156:157], v3 offset:43008
	ds_read_b64_tr_b16 v[158:159], v3 offset:47104
	s_waitcnt lgkmcnt(2)
	v_mfma_f32_32x32x16_bf16 v[84:99], v[148:151], v[152:155], v[84:99]
	ds_read_b64_tr_b16 v[152:153], v3 offset:43520
	ds_read_b64_tr_b16 v[154:155], v3 offset:47616
	s_waitcnt lgkmcnt(2)
	v_mfma_f32_32x32x16_bf16 v[68:83], v[148:151], v[156:159], v[68:83]
	ds_read_b64_tr_b16 v[156:157], v3 offset:44032
	ds_read_b64_tr_b16 v[158:159], v3 offset:48128
	s_waitcnt lgkmcnt(2)
	v_mfma_f32_32x32x16_bf16 v[52:67], v[148:151], v[152:155], v[52:67]
	ds_read_b64_tr_b16 v[152:153], v3 offset:44544
	ds_read_b64_tr_b16 v[154:155], v3 offset:48640
	s_waitcnt lgkmcnt(2)
	v_mfma_f32_32x32x16_bf16 v[36:51], v[148:151], v[156:159], v[36:51]
	s_waitcnt lgkmcnt(0)
	v_mfma_f32_32x32x16_bf16 v[20:35], v[148:151], v[152:155], v[20:35]
	ds_read_b128 v[180:183], v225 offset:4096
	ds_read_b128 v[184:187], v226 offset:4096
	s_waitcnt lgkmcnt(1)
	v_mfma_i32_32x32x32_i8 v[148:163], v[180:183], v[164:167], v[132:147]
	ds_read_b128 v[180:183], v227 offset:4096
	s_waitcnt lgkmcnt(1)
	v_mfma_i32_32x32x32_i8 v[148:163], v[184:187], v[168:171], v[148:163]
	ds_read_b128 v[188:191], v228 offset:4096
	s_waitcnt lgkmcnt(1)
	v_mfma_i32_32x32x32_i8 v[148:163], v[180:183], v[172:175], v[148:163]
	ds_read_b64_tr_b16 v[184:185], v3 offset:49152
	ds_read_b64_tr_b16 v[186:187], v3 offset:53248
	s_waitcnt lgkmcnt(2)
	v_mfma_i32_32x32x32_i8 v[148:163], v[188:191], v[176:179], v[148:163]
	ds_read_b64_tr_b16 v[180:181], v3 offset:49664
	ds_read_b64_tr_b16 v[182:183], v3 offset:53760
	s_nop 9
	v_max3_f32 v188, v148, v149, v150
	v_max3_f32 v189, v151, v152, v153
	v_max3_f32 v190, v154, v155, v156
	v_max3_f32 v191, v157, v158, v159
	v_max3_f32 v192, v160, v161, v162
	v_max3_f32 v188, v188, v189, v190
	v_max3_f32 v191, v191, v192, v163
	v_max_f32_e32 v188, v188, v191
	v_add_f32_e32 v188, 0xcb400000, v188
	v_fma_f32 v189, v207, v188, -v237
	v_cmp_gt_f32_e32 vcc, v189, v220
	s_cbranch_vccnz .Lv2_rare_h2
.Lv2_back_h2:
	v_mul_f32_e32 v189, v221, v207
	v_fma_f32 v190, s100, v189, v255
	v_fma_f32 v148, v148, v189, -v190
	v_fma_f32 v149, v149, v189, -v190
	v_exp_f32_e32 v148, v148
	v_fma_f32 v150, v150, v189, -v190
	v_exp_f32_e32 v149, v149
	v_fma_f32 v151, v151, v189, -v190
	v_exp_f32_e32 v150, v150
	v_fma_f32 v152, v152, v189, -v190
	v_exp_f32_e32 v151, v151
	v_fma_f32 v153, v153, v189, -v190
	v_exp_f32_e32 v152, v152
	v_fma_f32 v154, v154, v189, -v190
	v_exp_f32_e32 v153, v153
	v_fma_f32 v155, v155, v189, -v190
	v_exp_f32_e32 v154, v154
	v_fma_f32 v156, v156, v189, -v190
	v_exp_f32_e32 v155, v155
	v_fma_f32 v157, v157, v189, -v190
	v_exp_f32_e32 v156, v156
	v_fma_f32 v158, v158, v189, -v190
	v_exp_f32_e32 v157, v157
	v_fma_f32 v159, v159, v189, -v190
	v_exp_f32_e32 v158, v158
	v_fma_f32 v160, v160, v189, -v190
	v_exp_f32_e32 v159, v159
	v_fma_f32 v161, v161, v189, -v190
	v_exp_f32_e32 v160, v160
	v_fma_f32 v162, v162, v189, -v190
	v_exp_f32_e32 v161, v161
	v_fma_f32 v163, v163, v189, -v190
	v_exp_f32_e32 v162, v162
	v_exp_f32_e32 v163, v163
	v_add_f32_e32 v188, v148, v149
	v_add_f32_e32 v189, v150, v151
	v_add_f32_e32 v190, v152, v153
	v_add_f32_e32 v191, v154, v155
	v_add_f32_e32 v192, v156, v157
	v_add_f32_e32 v193, v158, v159
	v_add_f32_e32 v194, v160, v161
	v_add_f32_e32 v195, v162, v163
	v_add_f32_e32 v188, v188, v189
	v_add_f32_e32 v190, v190, v191
	v_add_f32_e32 v192, v192, v193
	v_add_f32_e32 v194, v194, v195
	v_add_f32_e32 v188, v188, v190
	v_add_f32_e32 v192, v192, v194
	v_add_f32_e32 v188, v188, v192
	v_add_f32_e32 v224, v224, v188
	v_cvt_pk_bf16_f32 v155, v154, v155
	v_cvt_pk_bf16_f32 v154, v152, v153
	v_cvt_pk_bf16_f32 v152, v148, v149
	v_cvt_pk_bf16_f32 v153, v150, v151
	v_cvt_pk_bf16_f32 v148, v156, v157
	v_cvt_pk_bf16_f32 v149, v158, v159
	v_cvt_pk_bf16_f32 v150, v160, v161
	v_cvt_pk_bf16_f32 v151, v162, v163
	s_waitcnt lgkmcnt(2)
	v_mfma_f32_32x32x16_bf16 v[4:19], v[152:155], v[184:187], v[4:19]
	ds_read_b64_tr_b16 v[156:157], v3 offset:50176
	ds_read_b64_tr_b16 v[158:159], v3 offset:54272
	s_waitcnt lgkmcnt(2)
	v_mfma_f32_32x32x16_bf16 v[116:131], v[152:155], v[180:183], v[116:131]
	ds_read_b64_tr_b16 v[160:161], v3 offset:50688
	ds_read_b64_tr_b16 v[162:163], v3 offset:54784
	s_waitcnt lgkmcnt(2)
	v_mfma_f32_32x32x16_bf16 v[100:115], v[152:155], v[156:159], v[100:115]
	ds_read_b64_tr_b16 v[156:157], v3 offset:51200
	ds_read_b64_tr_b16 v[158:159], v3 offset:55296
	s_waitcnt lgkmcnt(2)
	v_mfma_f32_32x32x16_bf16 v[84:99], v[152:155], v[160:163], v[84:99]
	ds_read_b64_tr_b16 v[160:161], v3 offset:51712
	ds_read_b64_tr_b16 v[162:163], v3 offset:55808
	s_waitcnt lgkmcnt(2)
	v_mfma_f32_32x32x16_bf16 v[68:83], v[152:155], v[156:159], v[68:83]
	ds_read_b64_tr_b16 v[156:157], v3 offset:52224
	ds_read_b64_tr_b16 v[158:159], v3 offset:56320
	s_waitcnt lgkmcnt(2)
	v_mfma_f32_32x32x16_bf16 v[52:67], v[152:155], v[160:163], v[52:67]
	ds_read_b64_tr_b16 v[160:161], v3 offset:52736
	ds_read_b64_tr_b16 v[162:163], v3 offset:56832
	s_waitcnt lgkmcnt(2)
	v_mfma_f32_32x32x16_bf16 v[36:51], v[152:155], v[156:159], v[36:51]
	ds_read_b64_tr_b16 v[156:157], v3 offset:57344
	ds_read_b64_tr_b16 v[158:159], v3 offset:61440
	s_waitcnt lgkmcnt(2)
	v_mfma_f32_32x32x16_bf16 v[20:35], v[152:155], v[160:163], v[20:35]
	ds_read_b64_tr_b16 v[152:153], v3 offset:57856
	ds_read_b64_tr_b16 v[154:155], v3 offset:61952
	s_waitcnt lgkmcnt(2)
	v_mfma_f32_32x32x16_bf16 v[4:19], v[148:151], v[156:159], v[4:19]
	ds_read_b64_tr_b16 v[156:157], v3 offset:58368
	ds_read_b64_tr_b16 v[158:159], v3 offset:62464
	s_waitcnt lgkmcnt(2)
	v_mfma_f32_32x32x16_bf16 v[116:131], v[148:151], v[152:155], v[116:131]
	ds_read_b64_tr_b16 v[152:153], v3 offset:58880
	ds_read_b64_tr_b16 v[154:155], v3 offset:62976
	s_waitcnt lgkmcnt(2)
	v_mfma_f32_32x32x16_bf16 v[100:115], v[148:151], v[156:159], v[100:115]
	ds_read_b64_tr_b16 v[156:157], v3 offset:59392
	ds_read_b64_tr_b16 v[158:159], v3 offset:63488
	s_waitcnt lgkmcnt(2)
	v_mfma_f32_32x32x16_bf16 v[84:99], v[148:151], v[152:155], v[84:99]
	ds_read_b64_tr_b16 v[152:153], v3 offset:59904
	ds_read_b64_tr_b16 v[154:155], v3 offset:64000
	s_waitcnt lgkmcnt(2)
	v_mfma_f32_32x32x16_bf16 v[68:83], v[148:151], v[156:159], v[68:83]
	ds_read_b64_tr_b16 v[156:157], v3 offset:60416
	ds_read_b64_tr_b16 v[158:159], v3 offset:64512
	s_waitcnt lgkmcnt(2)
	v_mfma_f32_32x32x16_bf16 v[52:67], v[148:151], v[152:155], v[52:67]
	ds_read_b64_tr_b16 v[152:153], v3 offset:60928
	ds_read_b64_tr_b16 v[154:155], v3 offset:65024
	s_waitcnt lgkmcnt(2)
	v_mfma_f32_32x32x16_bf16 v[36:51], v[148:151], v[156:159], v[36:51]
	s_waitcnt lgkmcnt(0)
	v_mfma_f32_32x32x16_bf16 v[20:35], v[148:151], v[152:155], v[20:35]
	s_min_u32 s85, s79, s84
	s_lshl_b32 s4, s85, 6
	s_cmp_lt_u32 s85, 4
	s_cselect_b64 s[2:3], -1, 0
	s_add_i32 s88, s4, 0xffffff00
	s_and_b64 s[86:87], s[2:3], exec
	s_cselect_b32 s4, s4, s88
	s_cselect_b32 s88, s17, s73
	s_cselect_b32 s89, s16, s72
	s_lshl_b64 s[86:87], s[4:5], 7
	s_add_u32 s86, s89, s86
	s_addc_u32 s87, s88, s87
	s_lshl_b32 s88, s85, 1
	s_mov_b32 s89, s5
	s_lshl_b64 s[88:89], s[88:89], 2
	s_add_u32 s85, s18, s88
	s_addc_u32 s90, s19, s89
	s_add_u32 s88, s74, s88
	s_addc_u32 s89, s75, s89
	s_add_u32 s88, s88, 0xffffffe0
	s_addc_u32 s89, s89, -1
	s_and_b64 s[2:3], s[2:3], exec
	s_waitcnt vmcnt(0)
	v_mov_b32_e32 v236, v209
	s_cselect_b32 s3, s90, s89
	s_cselect_b32 s2, s85, s88
	s_waitcnt vmcnt(0) lgkmcnt(0)
	s_barrier
	global_load_dwordx2 v[206:207], v201, s[2:3]
	ds_read_b128 v[180:183], v225 offset:16384
	ds_read_b128 v[184:187], v226 offset:16384
	s_cselect_b32 s85, s21, s77
	s_cselect_b32 s88, s20, s76
	s_lshl_b64 s[2:3], s[4:5], 9
	s_add_u32 s2, s88, s2
	s_addc_u32 s3, s85, s3
	s_waitcnt lgkmcnt(1)
	v_mfma_i32_32x32x32_i8 v[148:163], v[180:183], v[164:167], v[132:147]
	ds_read_b128 v[180:183], v227 offset:16384
	v_lshl_add_u64 v[188:189], s[86:87], 0, v[200:201]
	s_mov_b32 s4, m0
	s_mov_b32 m0, s83
	s_nop 0
	global_load_lds_dwordx4 v[188:189], off
	s_mov_b32 m0, s4
	v_lshl_add_u64 v[192:193], s[2:3], 0, v[204:205]
	s_mov_b32 s2, m0
	s_mov_b32 m0, s82
	s_nop 0
	global_load_lds_dwordx4 v[192:193], off
	s_mov_b32 m0, s2
	s_waitcnt lgkmcnt(1)
	v_mfma_i32_32x32x32_i8 v[148:163], v[184:187], v[168:171], v[148:163]
	ds_read_b128 v[188:191], v228 offset:16384
	v_lshl_add_u64 v[184:185], v[192:193], 0, s[6:7]
	s_add_i32 s2, s82, 0x400
	s_mov_b32 s3, m0
	s_mov_b32 m0, s2
	s_nop 0
	global_load_lds_dwordx4 v[184:185], off
	s_mov_b32 m0, s3
	v_lshl_add_u64 v[184:185], v[192:193], 0, s[8:9]
	s_add_i32 s2, s82, 0x800
	s_mov_b32 s3, m0
	s_mov_b32 m0, s2
	s_nop 0
	global_load_lds_dwordx4 v[184:185], off
	s_mov_b32 m0, s3
	s_waitcnt lgkmcnt(1)
	v_mfma_i32_32x32x32_i8 v[148:163], v[180:183], v[172:175], v[148:163]
	v_lshl_add_u64 v[180:181], v[192:193], 0, s[10:11]
	s_add_i32 s2, s82, 0xc00
	s_mov_b32 s3, m0
	s_mov_b32 m0, s2
	s_nop 0
	global_load_lds_dwordx4 v[180:181], off
	s_mov_b32 m0, s3
	ds_read_b64_tr_b16 v[184:185], v222 offset:32768
	ds_read_b64_tr_b16 v[186:187], v222 offset:36864
	s_waitcnt lgkmcnt(2)
	v_mfma_i32_32x32x32_i8 v[148:163], v[188:191], v[176:179], v[148:163]
	ds_read_b64_tr_b16 v[180:181], v222 offset:33280
	ds_read_b64_tr_b16 v[182:183], v222 offset:37376
	s_nop 9
	s_mov_b32 s90, s94
	v_max3_f32 v188, v148, v149, v150
	v_max3_f32 v189, v151, v152, v153
	v_max3_f32 v190, v154, v155, v156
	v_max3_f32 v191, v157, v158, v159
	v_max3_f32 v192, v160, v161, v162
	v_max3_f32 v188, v188, v189, v190
	v_max3_f32 v191, v191, v192, v163
	v_max_f32_e32 v188, v188, v191
	v_add_f32_e32 v188, 0xcb400000, v188
	v_fma_f32 v189, v208, v188, -v237
	v_cmp_gt_f32_e32 vcc, v189, v220
	s_cbranch_vccnz .Lv2_rare_h3
.Lv2_back_h3:
	v_mul_f32_e32 v189, v221, v208
	v_fma_f32 v190, s100, v189, v255
	v_fma_f32 v148, v148, v189, -v190
	v_fma_f32 v149, v149, v189, -v190
	v_exp_f32_e32 v148, v148
	v_fma_f32 v150, v150, v189, -v190
	v_exp_f32_e32 v149, v149
	v_fma_f32 v151, v151, v189, -v190
	v_exp_f32_e32 v150, v150
	v_fma_f32 v152, v152, v189, -v190
	v_exp_f32_e32 v151, v151
	v_fma_f32 v153, v153, v189, -v190
	v_exp_f32_e32 v152, v152
	v_fma_f32 v154, v154, v189, -v190
	v_exp_f32_e32 v153, v153
	v_fma_f32 v155, v155, v189, -v190
	v_exp_f32_e32 v154, v154
	v_fma_f32 v156, v156, v189, -v190
	v_exp_f32_e32 v155, v155
	v_fma_f32 v157, v157, v189, -v190
	v_exp_f32_e32 v156, v156
	v_fma_f32 v158, v158, v189, -v190
	v_exp_f32_e32 v157, v157
	v_fma_f32 v159, v159, v189, -v190
	v_exp_f32_e32 v158, v158
	v_fma_f32 v160, v160, v189, -v190
	v_exp_f32_e32 v159, v159
	v_fma_f32 v161, v161, v189, -v190
	v_exp_f32_e32 v160, v160
	v_fma_f32 v162, v162, v189, -v190
	v_exp_f32_e32 v161, v161
	v_fma_f32 v163, v163, v189, -v190
	v_exp_f32_e32 v162, v162
	v_exp_f32_e32 v163, v163
	v_add_f32_e32 v188, v148, v149
	v_add_f32_e32 v189, v150, v151
	v_add_f32_e32 v190, v152, v153
	v_add_f32_e32 v191, v154, v155
	v_add_f32_e32 v192, v156, v157
	v_add_f32_e32 v193, v158, v159
	v_add_f32_e32 v194, v160, v161
	v_add_f32_e32 v195, v162, v163
	v_add_f32_e32 v188, v188, v189
	v_add_f32_e32 v190, v190, v191
	v_add_f32_e32 v192, v192, v193
	v_add_f32_e32 v194, v194, v195
	v_add_f32_e32 v188, v188, v190
	v_add_f32_e32 v192, v192, v194
	v_add_f32_e32 v188, v188, v192
	v_add_f32_e32 v224, v224, v188
	v_cvt_pk_bf16_f32 v155, v154, v155
	v_cvt_pk_bf16_f32 v154, v152, v153
	v_cvt_pk_bf16_f32 v152, v148, v149
	v_cvt_pk_bf16_f32 v153, v150, v151
	v_cvt_pk_bf16_f32 v148, v156, v157
	v_cvt_pk_bf16_f32 v149, v158, v159
	v_cvt_pk_bf16_f32 v150, v160, v161
	v_cvt_pk_bf16_f32 v151, v162, v163
	s_waitcnt lgkmcnt(2)
	v_mfma_f32_32x32x16_bf16 v[4:19], v[152:155], v[184:187], v[4:19]
	ds_read_b64_tr_b16 v[156:157], v222 offset:33792
	ds_read_b64_tr_b16 v[158:159], v222 offset:37888
	s_waitcnt lgkmcnt(2)
	v_mfma_f32_32x32x16_bf16 v[116:131], v[152:155], v[180:183], v[116:131]
	ds_read_b64_tr_b16 v[160:161], v222 offset:34304
	ds_read_b64_tr_b16 v[162:163], v222 offset:38400
	s_waitcnt lgkmcnt(2)
	v_mfma_f32_32x32x16_bf16 v[100:115], v[152:155], v[156:159], v[100:115]
	ds_read_b64_tr_b16 v[156:157], v222 offset:34816
	ds_read_b64_tr_b16 v[158:159], v222 offset:38912
	s_waitcnt lgkmcnt(2)
	v_mfma_f32_32x32x16_bf16 v[84:99], v[152:155], v[160:163], v[84:99]
	ds_read_b64_tr_b16 v[160:161], v222 offset:35328
	ds_read_b64_tr_b16 v[162:163], v222 offset:39424
	s_waitcnt lgkmcnt(2)
	v_mfma_f32_32x32x16_bf16 v[68:83], v[152:155], v[156:159], v[68:83]
	ds_read_b64_tr_b16 v[156:157], v222 offset:35840
	ds_read_b64_tr_b16 v[158:159], v222 offset:39936
	s_waitcnt lgkmcnt(2)
	v_mfma_f32_32x32x16_bf16 v[52:67], v[152:155], v[160:163], v[52:67]
	ds_read_b64_tr_b16 v[160:161], v222 offset:36352
	ds_read_b64_tr_b16 v[162:163], v222 offset:40448
	s_waitcnt lgkmcnt(2)
	v_mfma_f32_32x32x16_bf16 v[36:51], v[152:155], v[156:159], v[36:51]
	ds_read_b64_tr_b16 v[156:157], v222 offset:40960
	ds_read_b64_tr_b16 v[158:159], v222 offset:45056
	s_waitcnt lgkmcnt(2)
	v_mfma_f32_32x32x16_bf16 v[20:35], v[152:155], v[160:163], v[20:35]
	ds_read_b64_tr_b16 v[152:153], v222 offset:41472
	ds_read_b64_tr_b16 v[154:155], v222 offset:45568
	s_waitcnt lgkmcnt(2)
	v_mfma_f32_32x32x16_bf16 v[4:19], v[148:151], v[156:159], v[4:19]
	ds_read_b64_tr_b16 v[156:157], v222 offset:41984
	ds_read_b64_tr_b16 v[158:159], v222 offset:46080
	s_waitcnt lgkmcnt(2)
	v_mfma_f32_32x32x16_bf16 v[116:131], v[148:151], v[152:155], v[116:131]
	ds_read_b64_tr_b16 v[152:153], v222 offset:42496
	ds_read_b64_tr_b16 v[154:155], v222 offset:46592
	s_waitcnt lgkmcnt(2)
	v_mfma_f32_32x32x16_bf16 v[100:115], v[148:151], v[156:159], v[100:115]
	ds_read_b64_tr_b16 v[156:157], v222 offset:43008
	ds_read_b64_tr_b16 v[158:159], v222 offset:47104
	s_waitcnt lgkmcnt(2)
	v_mfma_f32_32x32x16_bf16 v[84:99], v[148:151], v[152:155], v[84:99]
	ds_read_b64_tr_b16 v[152:153], v222 offset:43520
	ds_read_b64_tr_b16 v[154:155], v222 offset:47616
	s_waitcnt lgkmcnt(2)
	v_mfma_f32_32x32x16_bf16 v[68:83], v[148:151], v[156:159], v[68:83]
	ds_read_b64_tr_b16 v[156:157], v222 offset:44032
	ds_read_b64_tr_b16 v[158:159], v222 offset:48128
	s_waitcnt lgkmcnt(2)
	v_mfma_f32_32x32x16_bf16 v[52:67], v[148:151], v[152:155], v[52:67]
	ds_read_b64_tr_b16 v[152:153], v222 offset:44544
	ds_read_b64_tr_b16 v[154:155], v222 offset:48640
	s_waitcnt lgkmcnt(2)
	v_mfma_f32_32x32x16_bf16 v[36:51], v[148:151], v[156:159], v[36:51]
	s_waitcnt lgkmcnt(0)
	v_mfma_f32_32x32x16_bf16 v[20:35], v[148:151], v[152:155], v[20:35]
	ds_read_b128 v[180:183], v225 offset:20480
	ds_read_b128 v[184:187], v226 offset:20480
	s_waitcnt lgkmcnt(1)
	v_mfma_i32_32x32x32_i8 v[148:163], v[180:183], v[164:167], v[132:147]
	ds_read_b128 v[180:183], v227 offset:20480
	s_waitcnt lgkmcnt(1)
	v_mfma_i32_32x32x32_i8 v[148:163], v[184:187], v[168:171], v[148:163]
	ds_read_b128 v[188:191], v228 offset:20480
	s_waitcnt lgkmcnt(1)
	v_mfma_i32_32x32x32_i8 v[148:163], v[180:183], v[172:175], v[148:163]
	ds_read_b64_tr_b16 v[184:185], v222 offset:49152
	ds_read_b64_tr_b16 v[186:187], v222 offset:53248
	s_waitcnt lgkmcnt(2)
	v_mfma_i32_32x32x32_i8 v[148:163], v[188:191], v[176:179], v[148:163]
	ds_read_b64_tr_b16 v[180:181], v222 offset:49664
	ds_read_b64_tr_b16 v[182:183], v222 offset:53760
	s_nop 9
	v_max3_f32 v188, v148, v149, v150
	v_max3_f32 v189, v151, v152, v153
	v_max3_f32 v190, v154, v155, v156
	v_max3_f32 v191, v157, v158, v159
	v_max3_f32 v192, v160, v161, v162
	v_max3_f32 v188, v188, v189, v190
	v_max3_f32 v191, v191, v192, v163
	v_max_f32_e32 v188, v188, v191
	v_add_f32_e32 v188, 0xcb400000, v188
	v_fma_f32 v189, v236, v188, -v237
	v_cmp_gt_f32_e32 vcc, v189, v220
	s_cbranch_vccnz .Lv2_rare_h4
.Lv2_back_h4:
	v_mul_f32_e32 v189, v221, v236
	v_fma_f32 v190, s100, v189, v255
	v_fma_f32 v148, v148, v189, -v190
	v_fma_f32 v149, v149, v189, -v190
	v_exp_f32_e32 v148, v148
	v_fma_f32 v150, v150, v189, -v190
	v_exp_f32_e32 v149, v149
	v_fma_f32 v151, v151, v189, -v190
	v_exp_f32_e32 v150, v150
	v_fma_f32 v152, v152, v189, -v190
	v_exp_f32_e32 v151, v151
	v_fma_f32 v153, v153, v189, -v190
	v_exp_f32_e32 v152, v152
	v_fma_f32 v154, v154, v189, -v190
	v_exp_f32_e32 v153, v153
	v_fma_f32 v155, v155, v189, -v190
	v_exp_f32_e32 v154, v154
	v_fma_f32 v156, v156, v189, -v190
	v_exp_f32_e32 v155, v155
	v_fma_f32 v157, v157, v189, -v190
	v_exp_f32_e32 v156, v156
	v_fma_f32 v158, v158, v189, -v190
	v_exp_f32_e32 v157, v157
	v_fma_f32 v159, v159, v189, -v190
	v_exp_f32_e32 v158, v158
	v_fma_f32 v160, v160, v189, -v190
	v_exp_f32_e32 v159, v159
	v_fma_f32 v161, v161, v189, -v190
	v_exp_f32_e32 v160, v160
	v_fma_f32 v162, v162, v189, -v190
	v_exp_f32_e32 v161, v161
	v_fma_f32 v163, v163, v189, -v190
	v_exp_f32_e32 v162, v162
	v_exp_f32_e32 v163, v163
	v_add_f32_e32 v188, v148, v149
	v_add_f32_e32 v189, v150, v151
	v_add_f32_e32 v190, v152, v153
	v_add_f32_e32 v191, v154, v155
	v_add_f32_e32 v192, v156, v157
	v_add_f32_e32 v193, v158, v159
	v_add_f32_e32 v194, v160, v161
	v_add_f32_e32 v195, v162, v163
	v_add_f32_e32 v188, v188, v189
	v_add_f32_e32 v190, v190, v191
	v_add_f32_e32 v192, v192, v193
	v_add_f32_e32 v194, v194, v195
	v_add_f32_e32 v188, v188, v190
	v_add_f32_e32 v192, v192, v194
	v_add_f32_e32 v188, v188, v192
	v_add_f32_e32 v224, v224, v188
	v_cvt_pk_bf16_f32 v155, v154, v155
	v_cvt_pk_bf16_f32 v154, v152, v153
	v_cvt_pk_bf16_f32 v152, v148, v149
	v_cvt_pk_bf16_f32 v153, v150, v151
	v_cvt_pk_bf16_f32 v148, v156, v157
	v_cvt_pk_bf16_f32 v149, v158, v159
	v_cvt_pk_bf16_f32 v150, v160, v161
	v_cvt_pk_bf16_f32 v151, v162, v163
	s_waitcnt lgkmcnt(2)
	v_mfma_f32_32x32x16_bf16 v[4:19], v[152:155], v[184:187], v[4:19]
	ds_read_b64_tr_b16 v[156:157], v222 offset:50176
	ds_read_b64_tr_b16 v[158:159], v222 offset:54272
	s_waitcnt lgkmcnt(2)
	v_mfma_f32_32x32x16_bf16 v[116:131], v[152:155], v[180:183], v[116:131]
	ds_read_b64_tr_b16 v[160:161], v222 offset:50688
	ds_read_b64_tr_b16 v[162:163], v222 offset:54784
	s_waitcnt lgkmcnt(2)
	v_mfma_f32_32x32x16_bf16 v[100:115], v[152:155], v[156:159], v[100:115]
	ds_read_b64_tr_b16 v[156:157], v222 offset:51200
	ds_read_b64_tr_b16 v[158:159], v222 offset:55296
	s_waitcnt lgkmcnt(2)
	v_mfma_f32_32x32x16_bf16 v[84:99], v[152:155], v[160:163], v[84:99]
	ds_read_b64_tr_b16 v[160:161], v222 offset:51712
	ds_read_b64_tr_b16 v[162:163], v222 offset:55808
	s_waitcnt lgkmcnt(2)
	v_mfma_f32_32x32x16_bf16 v[68:83], v[152:155], v[156:159], v[68:83]
	ds_read_b64_tr_b16 v[156:157], v222 offset:52224
	ds_read_b64_tr_b16 v[158:159], v222 offset:56320
	s_waitcnt lgkmcnt(2)
	v_mfma_f32_32x32x16_bf16 v[52:67], v[152:155], v[160:163], v[52:67]
	ds_read_b64_tr_b16 v[160:161], v222 offset:52736
	ds_read_b64_tr_b16 v[162:163], v222 offset:56832
	s_waitcnt lgkmcnt(2)
	v_mfma_f32_32x32x16_bf16 v[36:51], v[152:155], v[156:159], v[36:51]
	ds_read_b64_tr_b16 v[156:157], v222 offset:57344
	ds_read_b64_tr_b16 v[158:159], v222 offset:61440
	s_waitcnt lgkmcnt(2)
; __device__ __forceinline__ void attn_unit256q(const bf16* __restrict__ Qb, const unsigned char* __restrict__ Kc, const unsigned char* __restrict__ Kl, const float* __restrict__ Sc, const float* __restrict__ Sl, ...
;     ...
;   for (int j = 0; j < NT; j += 2) {
;     A5_TILE(0, 0, KBUF, VBUF, j);
;     A5_TILE(KBUF, VBUF, 0, 0, j + 1);
;   }
	v_mfma_f32_32x32x16_bf16 v[20:35], v[152:155], v[160:163], v[20:35]
	ds_read_b64_tr_b16 v[152:153], v222 offset:57856
	ds_read_b64_tr_b16 v[154:155], v222 offset:61952
	s_waitcnt lgkmcnt(2)
	v_mfma_f32_32x32x16_bf16 v[4:19], v[148:151], v[156:159], v[4:19]
	ds_read_b64_tr_b16 v[156:157], v222 offset:58368
	ds_read_b64_tr_b16 v[158:159], v222 offset:62464
	s_waitcnt lgkmcnt(2)
	v_mfma_f32_32x32x16_bf16 v[116:131], v[148:151], v[152:155], v[116:131]
	ds_read_b64_tr_b16 v[152:153], v222 offset:58880
	ds_read_b64_tr_b16 v[154:155], v222 offset:62976
	s_waitcnt lgkmcnt(2)
	v_mfma_f32_32x32x16_bf16 v[100:115], v[148:151], v[156:159], v[100:115]
	ds_read_b64_tr_b16 v[156:157], v222 offset:59392
	ds_read_b64_tr_b16 v[158:159], v222 offset:63488
	s_waitcnt lgkmcnt(2)
	v_mfma_f32_32x32x16_bf16 v[84:99], v[148:151], v[152:155], v[84:99]
	ds_read_b64_tr_b16 v[152:153], v222 offset:59904
	ds_read_b64_tr_b16 v[154:155], v222 offset:64000
	s_waitcnt lgkmcnt(2)
	v_mfma_f32_32x32x16_bf16 v[68:83], v[148:151], v[156:159], v[68:83]
	ds_read_b64_tr_b16 v[156:157], v222 offset:60416
	ds_read_b64_tr_b16 v[158:159], v222 offset:64512
	s_waitcnt lgkmcnt(2)
	v_mfma_f32_32x32x16_bf16 v[52:67], v[148:151], v[152:155], v[52:67]
	ds_read_b64_tr_b16 v[152:153], v222 offset:60928
	ds_read_b64_tr_b16 v[154:155], v222 offset:65024
	s_waitcnt lgkmcnt(2)
	v_mfma_f32_32x32x16_bf16 v[36:51], v[148:151], v[156:159], v[36:51]
	s_waitcnt lgkmcnt(0)
	v_mfma_f32_32x32x16_bf16 v[20:35], v[148:151], v[152:155], v[20:35]
	s_add_i32 s2, s79, 2
	s_cmp_ge_u32 s79, s70
	s_cbranch_scc1 .LBB0_557
	s_mov_b32 s79, s2
	s_branch .LBB0_538
.Lv2_rare_h1:
	v_mov_b32_e32 v189, v188
	s_nop 1
	v_permlane32_swap_b32_e32 v188, v189
	v_max_f32_e32 v188, v188, v189
	v_mul_f32_e32 v189, v206, v188
	v_fma_f32 v188, v206, v188, -v237
	v_max_f32_e32 v189, v237, v189
	v_cmp_gt_f32_e32 vcc, v188, v220
	s_nop 1
	v_cndmask_b32_e32 v189, v237, v189, vcc
	v_sub_f32_e32 v188, v237, v189
	v_mul_f32_e32 v188, v221, v188
	v_exp_f32_e32 v254, v188
	v_mov_b32_e32 v237, v189
	v_mul_f32_e32 v255, v221, v189
	v_mul_f32_e32 v224, v224, v254
	s_and_saveexec_b64 s[2:3], s[0:1]
	ds_write_b32 v223, v254
	s_or_b64 exec, exec, s[2:3]
	s_waitcnt lgkmcnt(0)
	v_add_u32_e32 v253, s78, v218
	ds_read_b128 v[244:247], v253 offset:96
	ds_read_b128 v[248:251], v253 offset:64
	s_waitcnt lgkmcnt(1)
	v_pk_mul_f32 v[16:17], v[16:17], v[244:245]
	v_pk_mul_f32 v[18:19], v[18:19], v[246:247]
	v_pk_mul_f32 v[128:129], v[128:129], v[244:245]
	v_pk_mul_f32 v[130:131], v[130:131], v[246:247]
	v_pk_mul_f32 v[112:113], v[112:113], v[244:245]
	v_pk_mul_f32 v[114:115], v[114:115], v[246:247]
	v_pk_mul_f32 v[96:97], v[96:97], v[244:245]
	v_pk_mul_f32 v[98:99], v[98:99], v[246:247]
	v_pk_mul_f32 v[80:81], v[80:81], v[244:245]
	v_pk_mul_f32 v[82:83], v[82:83], v[246:247]
	v_pk_mul_f32 v[64:65], v[64:65], v[244:245]
	v_pk_mul_f32 v[66:67], v[66:67], v[246:247]
	v_pk_mul_f32 v[48:49], v[48:49], v[244:245]
	v_pk_mul_f32 v[50:51], v[50:51], v[246:247]
	v_pk_mul_f32 v[32:33], v[32:33], v[244:245]
	v_pk_mul_f32 v[34:35], v[34:35], v[246:247]
	s_waitcnt lgkmcnt(0)
	v_pk_mul_f32 v[12:13], v[12:13], v[248:249]
	v_pk_mul_f32 v[14:15], v[14:15], v[250:251]
	v_pk_mul_f32 v[124:125], v[124:125], v[248:249]
	v_pk_mul_f32 v[126:127], v[126:127], v[250:251]
	v_pk_mul_f32 v[108:109], v[108:109], v[248:249]
	v_pk_mul_f32 v[110:111], v[110:111], v[250:251]
	v_pk_mul_f32 v[92:93], v[92:93], v[248:249]
	v_pk_mul_f32 v[94:95], v[94:95], v[250:251]
	v_pk_mul_f32 v[76:77], v[76:77], v[248:249]
	v_pk_mul_f32 v[78:79], v[78:79], v[250:251]
	v_pk_mul_f32 v[60:61], v[60:61], v[248:249]
	v_pk_mul_f32 v[62:63], v[62:63], v[250:251]
	v_pk_mul_f32 v[44:45], v[44:45], v[248:249]
	v_pk_mul_f32 v[46:47], v[46:47], v[250:251]
	v_pk_mul_f32 v[28:29], v[28:29], v[248:249]
	v_pk_mul_f32 v[30:31], v[30:31], v[250:251]
	ds_read_b128 v[244:247], v253 offset:32
	ds_read_b128 v[248:251], v253
	s_waitcnt lgkmcnt(1)
	v_pk_mul_f32 v[8:9], v[8:9], v[244:245]
	v_pk_mul_f32 v[10:11], v[10:11], v[246:247]
	v_pk_mul_f32 v[120:121], v[120:121], v[244:245]
	v_pk_mul_f32 v[122:123], v[122:123], v[246:247]
	v_pk_mul_f32 v[104:105], v[104:105], v[244:245]
	v_pk_mul_f32 v[106:107], v[106:107], v[246:247]
	v_pk_mul_f32 v[88:89], v[88:89], v[244:245]
	v_pk_mul_f32 v[90:91], v[90:91], v[246:247]
	v_pk_mul_f32 v[72:73], v[72:73], v[244:245]
	v_pk_mul_f32 v[74:75], v[74:75], v[246:247]
	v_pk_mul_f32 v[56:57], v[56:57], v[244:245]
	v_pk_mul_f32 v[58:59], v[58:59], v[246:247]
	v_pk_mul_f32 v[40:41], v[40:41], v[244:245]
	v_pk_mul_f32 v[42:43], v[42:43], v[246:247]
	v_pk_mul_f32 v[24:25], v[24:25], v[244:245]
	v_pk_mul_f32 v[26:27], v[26:27], v[246:247]
	s_waitcnt lgkmcnt(0)
	v_pk_mul_f32 v[4:5], v[4:5], v[248:249]
	v_pk_mul_f32 v[6:7], v[6:7], v[250:251]
	v_pk_mul_f32 v[116:117], v[116:117], v[248:249]
	v_pk_mul_f32 v[118:119], v[118:119], v[250:251]
	v_pk_mul_f32 v[100:101], v[100:101], v[248:249]
	v_pk_mul_f32 v[102:103], v[102:103], v[250:251]
	v_pk_mul_f32 v[84:85], v[84:85], v[248:249]
	v_pk_mul_f32 v[86:87], v[86:87], v[250:251]
	v_pk_mul_f32 v[68:69], v[68:69], v[248:249]
	v_pk_mul_f32 v[70:71], v[70:71], v[250:251]
	v_pk_mul_f32 v[52:53], v[52:53], v[248:249]
	v_pk_mul_f32 v[54:55], v[54:55], v[250:251]
	v_pk_mul_f32 v[36:37], v[36:37], v[248:249]
	v_pk_mul_f32 v[38:39], v[38:39], v[250:251]
	v_pk_mul_f32 v[20:21], v[20:21], v[248:249]
	v_pk_mul_f32 v[22:23], v[22:23], v[250:251]
	s_branch .Lv2_back_h1
.Lv2_rare_h2:
	v_mov_b32_e32 v189, v188
	s_nop 1
	v_permlane32_swap_b32_e32 v188, v189
	v_max_f32_e32 v188, v188, v189
	v_mul_f32_e32 v189, v207, v188
	v_fma_f32 v188, v207, v188, -v237
	v_max_f32_e32 v189, v237, v189
	v_cmp_gt_f32_e32 vcc, v188, v220
	s_nop 1
	v_cndmask_b32_e32 v189, v237, v189, vcc
	v_sub_f32_e32 v188, v237, v189
	v_mul_f32_e32 v188, v221, v188
	v_exp_f32_e32 v254, v188
	v_mov_b32_e32 v237, v189
	v_mul_f32_e32 v255, v221, v189
	v_mul_f32_e32 v224, v224, v254
	s_and_saveexec_b64 s[2:3], s[0:1]
	ds_write_b32 v223, v254
	s_or_b64 exec, exec, s[2:3]
	s_waitcnt lgkmcnt(0)
	v_add_u32_e32 v253, s78, v218
	ds_read_b128 v[244:247], v253 offset:96
	ds_read_b128 v[248:251], v253 offset:64
	s_waitcnt lgkmcnt(1)
	v_pk_mul_f32 v[16:17], v[16:17], v[244:245]
	v_pk_mul_f32 v[18:19], v[18:19], v[246:247]
	v_pk_mul_f32 v[128:129], v[128:129], v[244:245]
	v_pk_mul_f32 v[130:131], v[130:131], v[246:247]
	v_pk_mul_f32 v[112:113], v[112:113], v[244:245]
	v_pk_mul_f32 v[114:115], v[114:115], v[246:247]
	v_pk_mul_f32 v[96:97], v[96:97], v[244:245]
	v_pk_mul_f32 v[98:99], v[98:99], v[246:247]
	v_pk_mul_f32 v[80:81], v[80:81], v[244:245]
	v_pk_mul_f32 v[82:83], v[82:83], v[246:247]
	v_pk_mul_f32 v[64:65], v[64:65], v[244:245]
	v_pk_mul_f32 v[66:67], v[66:67], v[246:247]
	v_pk_mul_f32 v[48:49], v[48:49], v[244:245]
	v_pk_mul_f32 v[50:51], v[50:51], v[246:247]
	v_pk_mul_f32 v[32:33], v[32:33], v[244:245]
	v_pk_mul_f32 v[34:35], v[34:35], v[246:247]
	s_waitcnt lgkmcnt(0)
	v_pk_mul_f32 v[12:13], v[12:13], v[248:249]
	v_pk_mul_f32 v[14:15], v[14:15], v[250:251]
	v_pk_mul_f32 v[124:125], v[124:125], v[248:249]
	v_pk_mul_f32 v[126:127], v[126:127], v[250:251]
	v_pk_mul_f32 v[108:109], v[108:109], v[248:249]
	v_pk_mul_f32 v[110:111], v[110:111], v[250:251]
	v_pk_mul_f32 v[92:93], v[92:93], v[248:249]
	v_pk_mul_f32 v[94:95], v[94:95], v[250:251]
	v_pk_mul_f32 v[76:77], v[76:77], v[248:249]
	v_pk_mul_f32 v[78:79], v[78:79], v[250:251]
	v_pk_mul_f32 v[60:61], v[60:61], v[248:249]
	v_pk_mul_f32 v[62:63], v[62:63], v[250:251]
	v_pk_mul_f32 v[44:45], v[44:45], v[248:249]
	v_pk_mul_f32 v[46:47], v[46:47], v[250:251]
	v_pk_mul_f32 v[28:29], v[28:29], v[248:249]
	v_pk_mul_f32 v[30:31], v[30:31], v[250:251]
	ds_read_b128 v[244:247], v253 offset:32
	ds_read_b128 v[248:251], v253
	s_waitcnt lgkmcnt(1)
	v_pk_mul_f32 v[8:9], v[8:9], v[244:245]
	v_pk_mul_f32 v[10:11], v[10:11], v[246:247]
	v_pk_mul_f32 v[120:121], v[120:121], v[244:245]
	v_pk_mul_f32 v[122:123], v[122:123], v[246:247]
	v_pk_mul_f32 v[104:105], v[104:105], v[244:245]
	v_pk_mul_f32 v[106:107], v[106:107], v[246:247]
	v_pk_mul_f32 v[88:89], v[88:89], v[244:245]
	v_pk_mul_f32 v[90:91], v[90:91], v[246:247]
	v_pk_mul_f32 v[72:73], v[72:73], v[244:245]
	v_pk_mul_f32 v[74:75], v[74:75], v[246:247]
	v_pk_mul_f32 v[56:57], v[56:57], v[244:245]
	v_pk_mul_f32 v[58:59], v[58:59], v[246:247]
	v_pk_mul_f32 v[40:41], v[40:41], v[244:245]
	v_pk_mul_f32 v[42:43], v[42:43], v[246:247]
	v_pk_mul_f32 v[24:25], v[24:25], v[244:245]
	v_pk_mul_f32 v[26:27], v[26:27], v[246:247]
	s_waitcnt lgkmcnt(0)
	v_pk_mul_f32 v[4:5], v[4:5], v[248:249]
	v_pk_mul_f32 v[6:7], v[6:7], v[250:251]
	v_pk_mul_f32 v[116:117], v[116:117], v[248:249]
	v_pk_mul_f32 v[118:119], v[118:119], v[250:251]
	v_pk_mul_f32 v[100:101], v[100:101], v[248:249]
	v_pk_mul_f32 v[102:103], v[102:103], v[250:251]
	v_pk_mul_f32 v[84:85], v[84:85], v[248:249]
	v_pk_mul_f32 v[86:87], v[86:87], v[250:251]
	v_pk_mul_f32 v[68:69], v[68:69], v[248:249]
	v_pk_mul_f32 v[70:71], v[70:71], v[250:251]
	v_pk_mul_f32 v[52:53], v[52:53], v[248:249]
	v_pk_mul_f32 v[54:55], v[54:55], v[250:251]
	v_pk_mul_f32 v[36:37], v[36:37], v[248:249]
	v_pk_mul_f32 v[38:39], v[38:39], v[250:251]
	v_pk_mul_f32 v[20:21], v[20:21], v[248:249]
	v_pk_mul_f32 v[22:23], v[22:23], v[250:251]
	s_branch .Lv2_back_h2
.Lv2_rare_h3:
	v_mov_b32_e32 v189, v188
	s_nop 1
	v_permlane32_swap_b32_e32 v188, v189
	v_max_f32_e32 v188, v188, v189
	v_mul_f32_e32 v189, v208, v188
	v_fma_f32 v188, v208, v188, -v237
	v_max_f32_e32 v189, v237, v189
	v_cmp_gt_f32_e32 vcc, v188, v220
	s_nop 1
	v_cndmask_b32_e32 v189, v237, v189, vcc
	v_sub_f32_e32 v188, v237, v189
	v_mul_f32_e32 v188, v221, v188
	v_exp_f32_e32 v254, v188
	v_mov_b32_e32 v237, v189
	v_mul_f32_e32 v255, v221, v189
	v_mul_f32_e32 v224, v224, v254
	s_and_saveexec_b64 s[2:3], s[0:1]
	ds_write_b32 v223, v254
	s_or_b64 exec, exec, s[2:3]
	s_waitcnt lgkmcnt(0)
	v_add_u32_e32 v253, s78, v218
	ds_read_b128 v[244:247], v253 offset:96
	ds_read_b128 v[248:251], v253 offset:64
	s_waitcnt lgkmcnt(1)
	v_pk_mul_f32 v[16:17], v[16:17], v[244:245]
	v_pk_mul_f32 v[18:19], v[18:19], v[246:247]
	v_pk_mul_f32 v[128:129], v[128:129], v[244:245]
	v_pk_mul_f32 v[130:131], v[130:131], v[246:247]
	v_pk_mul_f32 v[112:113], v[112:113], v[244:245]
	v_pk_mul_f32 v[114:115], v[114:115], v[246:247]
	v_pk_mul_f32 v[96:97], v[96:97], v[244:245]
	v_pk_mul_f32 v[98:99], v[98:99], v[246:247]
	v_pk_mul_f32 v[80:81], v[80:81], v[244:245]
	v_pk_mul_f32 v[82:83], v[82:83], v[246:247]
	v_pk_mul_f32 v[64:65], v[64:65], v[244:245]
	v_pk_mul_f32 v[66:67], v[66:67], v[246:247]
	v_pk_mul_f32 v[48:49], v[48:49], v[244:245]
	v_pk_mul_f32 v[50:51], v[50:51], v[246:247]
	v_pk_mul_f32 v[32:33], v[32:33], v[244:245]
	v_pk_mul_f32 v[34:35], v[34:35], v[246:247]
	s_waitcnt lgkmcnt(0)
; __device__ __forceinline__ void attn_unit256q(const bf16* __restrict__ Qb, const unsigned char* __restrict__ Kc, const unsigned char* __restrict__ Kl, const float* __restrict__ Sc, const float* __restrict__ Sl, ...
;     ...
;   if (hi == 0) wsf[32 + r32] = l_reg;
	v_pk_mul_f32 v[12:13], v[12:13], v[248:249]
	v_pk_mul_f32 v[14:15], v[14:15], v[250:251]
	v_pk_mul_f32 v[124:125], v[124:125], v[248:249]
	v_pk_mul_f32 v[126:127], v[126:127], v[250:251]
	v_pk_mul_f32 v[108:109], v[108:109], v[248:249]
	v_pk_mul_f32 v[110:111], v[110:111], v[250:251]
	v_pk_mul_f32 v[92:93], v[92:93], v[248:249]
	v_pk_mul_f32 v[94:95], v[94:95], v[250:251]
	v_pk_mul_f32 v[76:77], v[76:77], v[248:249]
	v_pk_mul_f32 v[78:79], v[78:79], v[250:251]
	v_pk_mul_f32 v[60:61], v[60:61], v[248:249]
	v_pk_mul_f32 v[62:63], v[62:63], v[250:251]
	v_pk_mul_f32 v[44:45], v[44:45], v[248:249]
	v_pk_mul_f32 v[46:47], v[46:47], v[250:251]
	v_pk_mul_f32 v[28:29], v[28:29], v[248:249]
	v_pk_mul_f32 v[30:31], v[30:31], v[250:251]
	ds_read_b128 v[244:247], v253 offset:32
	ds_read_b128 v[248:251], v253
	s_waitcnt lgkmcnt(1)
	v_pk_mul_f32 v[8:9], v[8:9], v[244:245]
	v_pk_mul_f32 v[10:11], v[10:11], v[246:247]
	v_pk_mul_f32 v[120:121], v[120:121], v[244:245]
	v_pk_mul_f32 v[122:123], v[122:123], v[246:247]
	v_pk_mul_f32 v[104:105], v[104:105], v[244:245]
	v_pk_mul_f32 v[106:107], v[106:107], v[246:247]
	v_pk_mul_f32 v[88:89], v[88:89], v[244:245]
	v_pk_mul_f32 v[90:91], v[90:91], v[246:247]
	v_pk_mul_f32 v[72:73], v[72:73], v[244:245]
	v_pk_mul_f32 v[74:75], v[74:75], v[246:247]
	v_pk_mul_f32 v[56:57], v[56:57], v[244:245]
	v_pk_mul_f32 v[58:59], v[58:59], v[246:247]
	v_pk_mul_f32 v[40:41], v[40:41], v[244:245]
	v_pk_mul_f32 v[42:43], v[42:43], v[246:247]
	v_pk_mul_f32 v[24:25], v[24:25], v[244:245]
	v_pk_mul_f32 v[26:27], v[26:27], v[246:247]
	s_waitcnt lgkmcnt(0)
	v_pk_mul_f32 v[4:5], v[4:5], v[248:249]
	v_pk_mul_f32 v[6:7], v[6:7], v[250:251]
	v_pk_mul_f32 v[116:117], v[116:117], v[248:249]
	v_pk_mul_f32 v[118:119], v[118:119], v[250:251]
	v_pk_mul_f32 v[100:101], v[100:101], v[248:249]
	v_pk_mul_f32 v[102:103], v[102:103], v[250:251]
	v_pk_mul_f32 v[84:85], v[84:85], v[248:249]
	v_pk_mul_f32 v[86:87], v[86:87], v[250:251]
	v_pk_mul_f32 v[68:69], v[68:69], v[248:249]
	v_pk_mul_f32 v[70:71], v[70:71], v[250:251]
	v_pk_mul_f32 v[52:53], v[52:53], v[248:249]
	v_pk_mul_f32 v[54:55], v[54:55], v[250:251]
	v_pk_mul_f32 v[36:37], v[36:37], v[248:249]
	v_pk_mul_f32 v[38:39], v[38:39], v[250:251]
	v_pk_mul_f32 v[20:21], v[20:21], v[248:249]
	v_pk_mul_f32 v[22:23], v[22:23], v[250:251]
	s_branch .Lv2_back_h3
.Lv2_rare_h4:
	v_mov_b32_e32 v189, v188
	s_nop 1
	v_permlane32_swap_b32_e32 v188, v189
	v_max_f32_e32 v188, v188, v189
	v_mul_f32_e32 v189, v236, v188
	v_fma_f32 v188, v236, v188, -v237
	v_max_f32_e32 v189, v237, v189
	v_cmp_gt_f32_e32 vcc, v188, v220
	s_nop 1
	v_cndmask_b32_e32 v189, v237, v189, vcc
	v_sub_f32_e32 v188, v237, v189
	v_mul_f32_e32 v188, v221, v188
	v_exp_f32_e32 v254, v188
	v_mov_b32_e32 v237, v189
	v_mul_f32_e32 v255, v221, v189
	v_mul_f32_e32 v224, v224, v254
	s_and_saveexec_b64 s[2:3], s[0:1]
	ds_write_b32 v223, v254
	s_or_b64 exec, exec, s[2:3]
	s_waitcnt lgkmcnt(0)
	v_add_u32_e32 v253, s78, v218
	ds_read_b128 v[244:247], v253 offset:96
	ds_read_b128 v[248:251], v253 offset:64
	s_waitcnt lgkmcnt(1)
	v_pk_mul_f32 v[16:17], v[16:17], v[244:245]
	v_pk_mul_f32 v[18:19], v[18:19], v[246:247]
	v_pk_mul_f32 v[128:129], v[128:129], v[244:245]
	v_pk_mul_f32 v[130:131], v[130:131], v[246:247]
	v_pk_mul_f32 v[112:113], v[112:113], v[244:245]
	v_pk_mul_f32 v[114:115], v[114:115], v[246:247]
	v_pk_mul_f32 v[96:97], v[96:97], v[244:245]
	v_pk_mul_f32 v[98:99], v[98:99], v[246:247]
	v_pk_mul_f32 v[80:81], v[80:81], v[244:245]
	v_pk_mul_f32 v[82:83], v[82:83], v[246:247]
	v_pk_mul_f32 v[64:65], v[64:65], v[244:245]
	v_pk_mul_f32 v[66:67], v[66:67], v[246:247]
	v_pk_mul_f32 v[48:49], v[48:49], v[244:245]
	v_pk_mul_f32 v[50:51], v[50:51], v[246:247]
	v_pk_mul_f32 v[32:33], v[32:33], v[244:245]
	v_pk_mul_f32 v[34:35], v[34:35], v[246:247]
	s_waitcnt lgkmcnt(0)
	v_pk_mul_f32 v[12:13], v[12:13], v[248:249]
	v_pk_mul_f32 v[14:15], v[14:15], v[250:251]
	v_pk_mul_f32 v[124:125], v[124:125], v[248:249]
	v_pk_mul_f32 v[126:127], v[126:127], v[250:251]
	v_pk_mul_f32 v[108:109], v[108:109], v[248:249]
	v_pk_mul_f32 v[110:111], v[110:111], v[250:251]
	v_pk_mul_f32 v[92:93], v[92:93], v[248:249]
	v_pk_mul_f32 v[94:95], v[94:95], v[250:251]
	v_pk_mul_f32 v[76:77], v[76:77], v[248:249]
	v_pk_mul_f32 v[78:79], v[78:79], v[250:251]
	v_pk_mul_f32 v[60:61], v[60:61], v[248:249]
	v_pk_mul_f32 v[62:63], v[62:63], v[250:251]
	v_pk_mul_f32 v[44:45], v[44:45], v[248:249]
	v_pk_mul_f32 v[46:47], v[46:47], v[250:251]
	v_pk_mul_f32 v[28:29], v[28:29], v[248:249]
	v_pk_mul_f32 v[30:31], v[30:31], v[250:251]
	ds_read_b128 v[244:247], v253 offset:32
	ds_read_b128 v[248:251], v253
	s_waitcnt lgkmcnt(1)
	v_pk_mul_f32 v[8:9], v[8:9], v[244:245]
	v_pk_mul_f32 v[10:11], v[10:11], v[246:247]
	v_pk_mul_f32 v[120:121], v[120:121], v[244:245]
	v_pk_mul_f32 v[122:123], v[122:123], v[246:247]
	v_pk_mul_f32 v[104:105], v[104:105], v[244:245]
	v_pk_mul_f32 v[106:107], v[106:107], v[246:247]
	v_pk_mul_f32 v[88:89], v[88:89], v[244:245]
	v_pk_mul_f32 v[90:91], v[90:91], v[246:247]
	v_pk_mul_f32 v[72:73], v[72:73], v[244:245]
	v_pk_mul_f32 v[74:75], v[74:75], v[246:247]
	v_pk_mul_f32 v[56:57], v[56:57], v[244:245]
	v_pk_mul_f32 v[58:59], v[58:59], v[246:247]
	v_pk_mul_f32 v[40:41], v[40:41], v[244:245]
	v_pk_mul_f32 v[42:43], v[42:43], v[246:247]
	v_pk_mul_f32 v[24:25], v[24:25], v[244:245]
	v_pk_mul_f32 v[26:27], v[26:27], v[246:247]
	s_waitcnt lgkmcnt(0)
	v_pk_mul_f32 v[4:5], v[4:5], v[248:249]
	v_pk_mul_f32 v[6:7], v[6:7], v[250:251]
	v_pk_mul_f32 v[116:117], v[116:117], v[248:249]
	v_pk_mul_f32 v[118:119], v[118:119], v[250:251]
	v_pk_mul_f32 v[100:101], v[100:101], v[248:249]
	v_pk_mul_f32 v[102:103], v[102:103], v[250:251]
	v_pk_mul_f32 v[84:85], v[84:85], v[248:249]
	v_pk_mul_f32 v[86:87], v[86:87], v[250:251]
	v_pk_mul_f32 v[68:69], v[68:69], v[248:249]
	v_pk_mul_f32 v[70:71], v[70:71], v[250:251]
	v_pk_mul_f32 v[52:53], v[52:53], v[248:249]
	v_pk_mul_f32 v[54:55], v[54:55], v[250:251]
	v_pk_mul_f32 v[36:37], v[36:37], v[248:249]
	v_pk_mul_f32 v[38:39], v[38:39], v[250:251]
	v_pk_mul_f32 v[20:21], v[20:21], v[248:249]
	v_pk_mul_f32 v[22:23], v[22:23], v[250:251]
	s_branch .Lv2_back_h4
.LBB0_557:
	v_mov_b32_e32 v188, v224
	v_mov_b32_e32 v189, v224
	s_nop 1
	v_permlane32_swap_b32_e32 v188, v189
	v_add_f32_e32 v224, v188, v189
	s_and_saveexec_b64 s[2:3], s[0:1]
	s_cbranch_execz .LBB0_528
	ds_write_b32 v223, v224 offset:128
	s_branch .LBB0_528
